# attention loops: exp/sum/cvt of later key groups interleaved under PV MFMAs, K/V global loads issued under QK MFMAs, LDS staging writes under last PV group, cross-half max exchange only on rescale pat
# speedup vs baseline: 1.0174x; 1.0174x over previous
; #define LAS __attribute__((address_space(3)))
; template <bool DIFF> ...
;     ...
;             {
;                 bf16x8 kf[2][NS];
; #pragma unroll
;                 for (int kb = 0; kb < 2; ++kb)
; #pragma unroll
;                     for (int st = 0; st < NS; ++st) kf[kb][st] = *(const LAS bf16x8*)(kb_ + (kb * 32 + l32) * KROWB + (s * DQK + st * 16 + hi * 8) * 2);
;                 VLOAD(vfa, 0);
;                 __builtin_amdgcn_sched_barrier(0);
;                 __builtin_amdgcn_s_setprio(1);
; #pragma unroll
;                 for (int st = 0; st < NS; ++st) {
;                     pr[0] = __builtin_amdgcn_mfma_f32_32x32x16_bf16(kf[0][st], qf[st], st == 0 ? negm : pr[0], 0, 0, 0);
;                     pr[1] = __builtin_amdgcn_mfma_f32_32x32x16_bf16(kf[1][st], qf[st], st == 0 ? negm : pr[1], 0, 0, 0); }
;                 __builtin_amdgcn_s_setprio(0);
;             }
;             const int tp0 = (t == 0) ? -16 : (t - 1) * 64;
;             if (DIFF) {
;                 if (tp0 + 63 - qpos_w > -128) {
; #pragma unroll
;                     for (int kb = 0; kb < 2; ++kb)
; #pragma unroll
;                         for (int r = 0; r < 16; ++r) { const int kvi = kb * 32 + 8 * (r >> 2) + 4 * hi + (r & 3); int idx = tp0 + kvi - qpos + 128; idx = idx < 0 ? 0 : idx; pr[kb][r] += lut[idx]; }
;                 }
;             }
.LBB0_335:
	s_cmp_lt_u32 s45, s35
	s_mov_b64 s[0:1], -1
	s_cbranch_scc1 .LBB0_337
	s_add_i32 s46, s47, 64
	s_mov_b64 s[0:1], 0
.LBB0_337:
	s_andn2_b64 vcc, exec, s[0:1]
	s_and_b32 s0, s45, 1
	s_cbranch_vccnz .LBB0_342
	s_mul_i32 s1, s0, 0x9400
	s_add_i32 s1, s1, 0
	v_add_u32_e32 v96, s1, v215
	v_add3_u32 v97, s1, v214, v213
	v_add_u32_e32 v221, v96, v209
	ds_read_b128 v[80:83], v97
	ds_read_b128 v[84:87], v97 offset:32
	ds_read_b128 v[88:91], v97 offset:64
	ds_read_b128 v[92:95], v97 offset:96
	ds_read_b128 v[222:225], v97 offset:8704
	ds_read_b128 v[226:229], v97 offset:8736
	ds_read_b128 v[230:233], v97 offset:8768
	ds_read_b128 v[234:237], v97 offset:8800
	ds_read_b64_tr_b16 v[174:175], v221 offset:17408
	ds_read_b64_tr_b16 v[170:171], v221 offset:17472
	ds_read_b64_tr_b16 v[166:167], v221 offset:17536
	ds_read_b64_tr_b16 v[162:163], v221 offset:17600
	ds_read_b64_tr_b16 v[176:177], v221 offset:19968
	ds_read_b64_tr_b16 v[172:173], v221 offset:20032
	ds_read_b64_tr_b16 v[168:169], v221 offset:20096
	ds_read_b64_tr_b16 v[164:165], v221 offset:20160
	s_setprio 1
	s_waitcnt lgkmcnt(14)
	v_mfma_f32_32x32x16_bf16 v[112:127], v[80:83], v[142:145], v[64:79]
	s_waitcnt lgkmcnt(11)
	v_mfma_f32_32x32x16_bf16 v[96:111], v[222:225], v[142:145], v[64:79]
	v_add_u32_e32 v80, s47, v220
	v_ashrrev_i32_e32 v81, 31, v80
	v_add_u32_e32 v82, s47, v219
	v_lshlrev_b64 v[80:81], 11, v[80:81]
	v_mfma_f32_32x32x16_bf16 v[112:127], v[84:87], v[138:141], v[112:127]
	v_ashrrev_i32_e32 v83, 31, v82
	v_lshl_add_u64 v[80:81], v[190:191], 0, v[80:81]
	v_lshlrev_b64 v[82:83], 11, v[82:83]
	v_lshl_add_u64 v[82:83], v[192:193], 0, v[82:83]
	global_load_dwordx4 v[146:149], v[80:81], off
	global_load_dwordx4 v[150:153], v[82:83], off
	s_waitcnt lgkmcnt(10)
	v_mfma_f32_32x32x16_bf16 v[96:111], v[226:229], v[138:141], v[96:111]
	v_add_u32_e32 v80, s47, v218
	v_ashrrev_i32_e32 v81, 31, v80
	v_add_u32_e32 v82, s47, v217
	v_lshlrev_b64 v[80:81], 11, v[80:81]
	v_mfma_f32_32x32x16_bf16 v[112:127], v[88:91], v[134:137], v[112:127]
	v_ashrrev_i32_e32 v83, 31, v82
	v_lshl_add_u64 v[80:81], v[188:189], 0, v[80:81]
	v_lshlrev_b64 v[82:83], 11, v[82:83]
	v_lshl_add_u64 v[82:83], v[188:189], 0, v[82:83]
	global_load_dwordx4 v[154:157], v[80:81], off
	global_load_dwordx4 v[158:161], v[82:83], off
	s_waitcnt lgkmcnt(9)
	v_mfma_f32_32x32x16_bf16 v[96:111], v[230:233], v[134:137], v[96:111]
	v_mfma_f32_32x32x16_bf16 v[112:127], v[92:95], v[130:133], v[112:127]
	s_waitcnt lgkmcnt(8)
	v_mfma_f32_32x32x16_bf16 v[96:111], v[234:237], v[130:133], v[96:111]
	s_setprio 0
	s_add_i32 s46, s47, 64
	s_cmp_le_i32 s46, s44
	s_cbranch_scc1 .LBB0_340
	v_add_u32_e32 v200, s47, v216
	s_add_i32 s1, 0, 0x18000
	v_max_i32_e32 v222, 0xffffff5d, v200
	v_lshl_add_u32 v223, v222, 2, s1
	v_max_i32_e32 v222, 0xffffff58, v200
	v_max_i32_e32 v228, 0xffffff4f, v200
	v_lshl_add_u32 v224, v222, 2, s1
	v_max_i32_e32 v222, 0xffffff57, v200
	v_lshl_add_u32 v229, v228, 2, s1
	v_max_i32_e32 v228, 0xffffff4e, v200
	v_lshl_add_u32 v225, v222, 2, s1
	v_max_i32_e32 v222, 0xffffff56, v200
	v_lshl_add_u32 v230, v228, 2, s1
	v_max_i32_e32 v228, 0xffffff4d, v200
	v_max_i32_e32 v80, 0xffffff80, v200
	v_max_i32_e32 v81, 0xffffff7f, v200
	v_max_i32_e32 v82, 0xffffff7e, v200
	v_max_i32_e32 v83, 0xffffff7d, v200
	v_max_i32_e32 v84, 0xffffff78, v200
	v_max_i32_e32 v85, 0xffffff77, v200
	v_max_i32_e32 v86, 0xffffff76, v200
	v_max_i32_e32 v87, 0xffffff75, v200
	v_max_i32_e32 v88, 0xffffff70, v200
	v_max_i32_e32 v89, 0xffffff6f, v200
	v_max_i32_e32 v90, 0xffffff6e, v200
	v_max_i32_e32 v91, 0xffffff6d, v200
	v_max_i32_e32 v92, 0xffffff68, v200
	v_max_i32_e32 v93, 0xffffff67, v200
	v_max_i32_e32 v94, 0xffffff66, v200
	v_max_i32_e32 v95, 0xffffff65, v200
	v_max_i32_e32 v198, 0xffffff60, v200
	v_max_i32_e32 v199, 0xffffff5f, v200
	v_max_i32_e32 v201, 0xffffff5e, v200
	v_lshl_add_u32 v226, v222, 2, s1
	v_max_i32_e32 v222, 0xffffff55, v200
	v_lshl_add_u32 v231, v228, 2, s1
	v_max_i32_e32 v228, 0xffffff48, v200
	v_lshl_add_u32 v80, v80, 2, s1
	v_lshl_add_u32 v81, v81, 2, s1
	v_lshl_add_u32 v82, v82, 2, s1
	v_lshl_add_u32 v83, v83, 2, s1
	v_lshl_add_u32 v84, v84, 2, s1
	v_lshl_add_u32 v85, v85, 2, s1
	v_lshl_add_u32 v86, v86, 2, s1
	v_lshl_add_u32 v87, v87, 2, s1
	v_lshl_add_u32 v88, v88, 2, s1
	v_lshl_add_u32 v89, v89, 2, s1
	v_lshl_add_u32 v90, v90, 2, s1
	v_lshl_add_u32 v91, v91, 2, s1
	v_lshl_add_u32 v92, v92, 2, s1
	v_lshl_add_u32 v93, v93, 2, s1
	v_lshl_add_u32 v94, v94, 2, s1
	v_lshl_add_u32 v95, v95, 2, s1
	v_lshl_add_u32 v198, v198, 2, s1
	v_lshl_add_u32 v199, v199, 2, s1
	v_lshl_add_u32 v201, v201, 2, s1
	v_lshl_add_u32 v227, v222, 2, s1
	v_lshl_add_u32 v232, v228, 2, s1
	v_max_i32_e32 v228, 0xffffff47, v200
	ds_read_b32 v80, v80 offset:512
	ds_read_b32 v81, v81 offset:516
	ds_read_b32 v82, v82 offset:520
	ds_read_b32 v83, v83 offset:524
	ds_read_b32 v84, v84 offset:544
	ds_read_b32 v85, v85 offset:548
	ds_read_b32 v86, v86 offset:552
	ds_read_b32 v87, v87 offset:556
	ds_read_b32 v88, v88 offset:576
	ds_read_b32 v89, v89 offset:580
	ds_read_b32 v90, v90 offset:584
	ds_read_b32 v91, v91 offset:588
	ds_read_b32 v92, v92 offset:608
	ds_read_b32 v93, v93 offset:612
	ds_read_b32 v94, v94 offset:616
	ds_read_b32 v95, v95 offset:620
	ds_read_b32 v198, v198 offset:640
	ds_read_b32 v199, v199 offset:644
	ds_read_b32 v222, v201 offset:648
	ds_read_b32 v223, v223 offset:652
	ds_read_b32 v224, v224 offset:672
	ds_read_b32 v225, v225 offset:676
	ds_read_b32 v226, v226 offset:680
	ds_read_b32 v227, v227 offset:684
	v_max_i32_e32 v201, 0xffffff50, v200
	v_lshl_add_u32 v233, v228, 2, s1
	v_max_i32_e32 v228, 0xffffff46, v200
	v_lshl_add_u32 v201, v201, 2, s1
	v_lshl_add_u32 v234, v228, 2, s1
	v_max_i32_e32 v200, 0xffffff45, v200
	v_lshl_add_u32 v200, v200, 2, s1
	ds_read_b32 v228, v201 offset:704
	ds_read_b32 v229, v229 offset:708
	ds_read_b32 v230, v230 offset:712
	ds_read_b32 v231, v231 offset:716
	ds_read_b32 v232, v232 offset:736
	ds_read_b32 v233, v233 offset:740
	ds_read_b32 v234, v234 offset:744
	ds_read_b32 v235, v200 offset:748
	s_waitcnt lgkmcnt(14)
	v_pk_add_f32 v[126:127], v[126:127], v[94:95]
	v_pk_add_f32 v[124:125], v[124:125], v[92:93]
	v_pk_add_f32 v[122:123], v[122:123], v[90:91]
	v_pk_add_f32 v[120:121], v[120:121], v[88:89]
	v_pk_add_f32 v[118:119], v[118:119], v[86:87]
	v_pk_add_f32 v[116:117], v[116:117], v[84:85]
	v_pk_add_f32 v[114:115], v[114:115], v[82:83]
	v_pk_add_f32 v[112:113], v[112:113], v[80:81]
	s_waitcnt lgkmcnt(0)
	v_pk_add_f32 v[110:111], v[110:111], v[234:235]
	v_pk_add_f32 v[108:109], v[108:109], v[232:233]
	v_pk_add_f32 v[106:107], v[106:107], v[230:231]
	v_pk_add_f32 v[104:105], v[104:105], v[228:229]
	v_pk_add_f32 v[102:103], v[102:103], v[226:227]
	v_pk_add_f32 v[100:101], v[100:101], v[224:225]
	v_pk_add_f32 v[98:99], v[98:99], v[222:223]
	v_pk_add_f32 v[96:97], v[96:97], v[198:199]
; __device__ __forceinline__ float shx(float v, int mask, int lane) { return __int_as_float(__builtin_amdgcn_ds_bpermute((lane ^ mask) << 2, __float_as_int(v))); }
; template <bool DIFF> ...
;     ...
;             float mx;
;             { float a0 = fmaxf(fmaxf(pr[0][0], pr[0][1]), pr[0][2]), a1 = fmaxf(fmaxf(pr[1][0], pr[1][1]), pr[1][2]);
; #pragma unroll
;               for (int r = 3; r < 15; r += 2) { a0 = fmaxf(fmaxf(a0, pr[0][r]), pr[0][r + 1]); a1 = fmaxf(fmaxf(a1, pr[1][r]), pr[1][r + 1]); }
;               mx = fmaxf(fmaxf(a0, a1), fmaxf(pr[0][15], pr[1][15])); }
;             mx = fmaxf(mx, shx(mx, 32, lane));
;             if (t == 0 || __any(mx > 8.0f)) {
;                 const float dl = (t == 0) ? mx : fmaxf(mx, 0.f);
;                 mrun += dl;
; #pragma unroll
;                 for (int r = 0; r < 16; ++r) negm[r] = -mrun;
;                 const float alpha = (t == 0) ? 1.f : __builtin_amdgcn_exp2f(-dl); lsum *= alpha;
; #pragma unroll
;                 for (int kb = 0; kb < 2; ++kb) pr[kb] = pr[kb] - dl;
; #pragma unroll
;                 for (int db = 0; db < NDB; ++db) o[db] = o[db] * alpha;
;             }
.LBB0_340:
	s_nop 5
	v_max3_f32 v80, v112, v113, v114
	s_nop 0
	v_max3_f32 v81, v96, v97, v98
	v_max3_f32 v80, v80, v115, v116
	v_max3_f32 v81, v81, v99, v100
	v_max3_f32 v80, v80, v117, v118
	v_max3_f32 v81, v81, v101, v102
	v_max3_f32 v80, v80, v119, v120
	v_max3_f32 v81, v81, v103, v104
	v_max3_f32 v80, v80, v121, v122
	v_max3_f32 v81, v81, v105, v106
	v_max3_f32 v80, v80, v123, v124
	v_max3_f32 v81, v81, v107, v108
	v_max_f32_e32 v82, v111, v111
	v_max_f32_e32 v83, v127, v127
	v_max3_f32 v80, v80, v125, v126
	v_max3_f32 v81, v81, v109, v110
	v_max_f32_e32 v82, v83, v82
	v_max3_f32 v80, v80, v81, v82
	v_cmp_lt_f32_e32 vcc, s33, v80
	s_cbranch_vccz .LBB0_343
	ds_bpermute_b32 v81, v204, v80
	s_waitcnt lgkmcnt(0)
	v_max_f32_e32 v81, v81, v81
	v_max_f32_e32 v80, v80, v81
	v_max_f32_e32 v64, v80, v80
	v_max_f32_e32 v65, 0, v64
	v_exp_f32_e64 v66, -v65
	v_add_f32_e32 v186, v186, v65
	v_xor_b32_e32 v64, 0x80000000, v186
	v_sub_f32_e32 v112, v112, v65
	v_sub_f32_e32 v113, v113, v65
	v_sub_f32_e32 v114, v114, v65
	v_sub_f32_e32 v127, v127, v65
	v_sub_f32_e32 v115, v115, v65
	v_sub_f32_e32 v116, v116, v65
	v_sub_f32_e32 v117, v117, v65
	v_sub_f32_e32 v118, v118, v65
	v_sub_f32_e32 v119, v119, v65
	v_sub_f32_e32 v120, v120, v65
	v_sub_f32_e32 v121, v121, v65
	v_sub_f32_e32 v122, v122, v65
	v_sub_f32_e32 v123, v123, v65
	v_sub_f32_e32 v124, v124, v65
	v_sub_f32_e32 v125, v125, v65
	v_sub_f32_e32 v126, v126, v65
	v_sub_f32_e32 v96, v96, v65
	v_sub_f32_e32 v97, v97, v65
	v_sub_f32_e32 v98, v98, v65
	v_sub_f32_e32 v99, v99, v65
	v_sub_f32_e32 v100, v100, v65
	v_sub_f32_e32 v101, v101, v65
	v_sub_f32_e32 v102, v102, v65
	v_sub_f32_e32 v103, v103, v65
	v_sub_f32_e32 v104, v104, v65
	v_sub_f32_e32 v105, v105, v65
	v_sub_f32_e32 v106, v106, v65
	v_sub_f32_e32 v107, v107, v65
	v_sub_f32_e32 v108, v108, v65
	v_sub_f32_e32 v109, v109, v65
	v_sub_f32_e32 v110, v110, v65
	v_sub_f32_e32 v111, v111, v65
	v_pk_mul_f32 v[62:63], v[62:63], v[66:67] op_sel_hi:[1,0]
	v_pk_mul_f32 v[60:61], v[60:61], v[66:67] op_sel_hi:[1,0]
	v_pk_mul_f32 v[58:59], v[58:59], v[66:67] op_sel_hi:[1,0]
	v_pk_mul_f32 v[56:57], v[56:57], v[66:67] op_sel_hi:[1,0]
	v_pk_mul_f32 v[54:55], v[54:55], v[66:67] op_sel_hi:[1,0]
	v_pk_mul_f32 v[52:53], v[52:53], v[66:67] op_sel_hi:[1,0]
	v_pk_mul_f32 v[50:51], v[50:51], v[66:67] op_sel_hi:[1,0]
	v_pk_mul_f32 v[48:49], v[48:49], v[66:67] op_sel_hi:[1,0]
	v_pk_mul_f32 v[46:47], v[46:47], v[66:67] op_sel_hi:[1,0]
	v_pk_mul_f32 v[44:45], v[44:45], v[66:67] op_sel_hi:[1,0]
	v_pk_mul_f32 v[42:43], v[42:43], v[66:67] op_sel_hi:[1,0]
	v_pk_mul_f32 v[40:41], v[40:41], v[66:67] op_sel_hi:[1,0]
	v_pk_mul_f32 v[38:39], v[38:39], v[66:67] op_sel_hi:[1,0]
	v_pk_mul_f32 v[36:37], v[36:37], v[66:67] op_sel_hi:[1,0]
	v_pk_mul_f32 v[34:35], v[34:35], v[66:67] op_sel_hi:[1,0]
	v_pk_mul_f32 v[32:33], v[32:33], v[66:67] op_sel_hi:[1,0]
	v_pk_mul_f32 v[30:31], v[30:31], v[66:67] op_sel_hi:[1,0]
	v_pk_mul_f32 v[28:29], v[28:29], v[66:67] op_sel_hi:[1,0]
	v_pk_mul_f32 v[26:27], v[26:27], v[66:67] op_sel_hi:[1,0]
	v_pk_mul_f32 v[24:25], v[24:25], v[66:67] op_sel_hi:[1,0]
	v_pk_mul_f32 v[22:23], v[22:23], v[66:67] op_sel_hi:[1,0]
	v_pk_mul_f32 v[20:21], v[20:21], v[66:67] op_sel_hi:[1,0]
	v_pk_mul_f32 v[18:19], v[18:19], v[66:67] op_sel_hi:[1,0]
	v_pk_mul_f32 v[16:17], v[16:17], v[66:67] op_sel_hi:[1,0]
	v_pk_mul_f32 v[14:15], v[14:15], v[66:67] op_sel_hi:[1,0]
	v_pk_mul_f32 v[12:13], v[12:13], v[66:67] op_sel_hi:[1,0]
	v_pk_mul_f32 v[10:11], v[10:11], v[66:67] op_sel_hi:[1,0]
	v_pk_mul_f32 v[8:9], v[8:9], v[66:67] op_sel_hi:[1,0]
	v_pk_mul_f32 v[6:7], v[6:7], v[66:67] op_sel_hi:[1,0]
	v_pk_mul_f32 v[4:5], v[4:5], v[66:67] op_sel_hi:[1,0]
	v_pk_mul_f32 v[2:3], v[2:3], v[66:67] op_sel_hi:[1,0]
	v_pk_mul_f32 v[0:1], v[0:1], v[66:67] op_sel_hi:[1,0]
	v_mul_f32_e32 v187, v187, v66
	v_mov_b32_e32 v65, v64
	v_mov_b32_e32 v66, v64
	v_mov_b32_e32 v67, v64
	v_mov_b32_e32 v68, v64
	v_mov_b32_e32 v69, v64
	v_mov_b32_e32 v70, v64
	v_mov_b32_e32 v71, v64
	v_mov_b32_e32 v72, v64
	v_mov_b32_e32 v73, v64
	v_mov_b32_e32 v74, v64
	v_mov_b32_e32 v75, v64
	v_mov_b32_e32 v76, v64
	v_mov_b32_e32 v77, v64
	v_mov_b32_e32 v78, v64
	v_mov_b32_e32 v79, v64
	s_branch .LBB0_344
.LBB0_342:
	v_add_u32_e32 v80, s47, v220
	v_ashrrev_i32_e32 v81, 31, v80
	v_add_u32_e32 v82, s47, v219
	v_lshlrev_b64 v[80:81], 11, v[80:81]
	v_ashrrev_i32_e32 v83, 31, v82
	v_lshl_add_u64 v[80:81], v[190:191], 0, v[80:81]
	v_lshlrev_b64 v[82:83], 11, v[82:83]
	v_lshl_add_u64 v[82:83], v[192:193], 0, v[82:83]
	global_load_dwordx4 v[146:149], v[80:81], off
	global_load_dwordx4 v[150:153], v[82:83], off
	v_add_u32_e32 v80, s47, v218
	v_ashrrev_i32_e32 v81, 31, v80
	v_add_u32_e32 v82, s47, v217
	v_lshlrev_b64 v[80:81], 11, v[80:81]
	v_ashrrev_i32_e32 v83, 31, v82
	v_lshl_add_u64 v[80:81], v[188:189], 0, v[80:81]
	v_lshlrev_b64 v[82:83], 11, v[82:83]
	v_lshl_add_u64 v[82:83], v[188:189], 0, v[82:83]
	global_load_dwordx4 v[154:157], v[80:81], off
	global_load_dwordx4 v[158:161], v[82:83], off
	s_branch .LBB0_345
; template <bool DIFF> ...
;     ...
;             f32x2 ps2 = (f32x2){0.f, 0.f};
; #pragma unroll
;             for (int kb = 0; kb < 2; ++kb)
; #pragma unroll
;                 for (int r = 0; r < 16; r += 2) { const float e0 = __builtin_amdgcn_exp2f(pr[kb][r]), e1 = __builtin_amdgcn_exp2f(pr[kb][r + 1]); pr[kb][r] = e0; pr[kb][r + 1] = e1; ps2 += (f32x2){e0, e1}; }
;             lsum += ps2[0] + ps2[1];
;             __builtin_amdgcn_sched_barrier(0);
;             VLOAD(vfb, 1); __builtin_amdgcn_sched_barrier(0); PVMMA(vfa, 0); __builtin_amdgcn_sched_barrier(0);
;             VLOAD(vfa, 2); __builtin_amdgcn_sched_barrier(0); PVMMA(vfb, 1); __builtin_amdgcn_sched_barrier(0);
;             VLOAD(vfb, 3); __builtin_amdgcn_sched_barrier(0); PVMMA(vfa, 2); __builtin_amdgcn_sched_barrier(0);
;             PVMMA(vfb, 3);
;     ...
;         }
;         if (t + 1 < NT) ATT_LSTORE(buf ^ 1);
;         __syncthreads();
.LBB0_343:
.LBB0_344:
	ds_read_b64_tr_b16 v[224:225], v221 offset:22528
	ds_read_b64_tr_b16 v[228:229], v221 offset:22592
	ds_read_b64_tr_b16 v[232:233], v221 offset:22656
	ds_read_b64_tr_b16 v[92:93], v221 offset:22720
	ds_read_b64_tr_b16 v[226:227], v221 offset:25088
	ds_read_b64_tr_b16 v[230:231], v221 offset:25152
	ds_read_b64_tr_b16 v[234:235], v221 offset:25216
	ds_read_b64_tr_b16 v[94:95], v221 offset:25280
	v_exp_f32_e32 v236, v112
	v_exp_f32_e32 v237, v113
	v_exp_f32_e32 v112, v114
	v_exp_f32_e32 v113, v115
	v_pk_add_f32 v[222:223], v[236:237], 0 op_sel_hi:[1,0]
	v_exp_f32_e32 v114, v116
	v_exp_f32_e32 v115, v117
	v_pk_add_f32 v[222:223], v[112:113], v[222:223]
	v_exp_f32_e32 v116, v118
	v_exp_f32_e32 v117, v119
	v_pk_add_f32 v[222:223], v[114:115], v[222:223]
	v_cvt_pk_bf16_f32 v88, v236, v237
	v_cvt_pk_bf16_f32 v89, v112, v113
	v_cvt_pk_bf16_f32 v90, v114, v115
	v_cvt_pk_bf16_f32 v91, v116, v117
	s_setprio 1
	v_pk_add_f32 v[222:223], v[116:117], v[222:223]
	s_waitcnt lgkmcnt(8)
	v_mfma_f32_32x32x16_bf16 v[48:63], v[174:177], v[88:91], v[48:63]
	v_exp_f32_e32 v118, v120
	v_exp_f32_e32 v119, v121
	v_mfma_f32_32x32x16_bf16 v[32:47], v[170:173], v[88:91], v[32:47]
	v_exp_f32_e32 v120, v122
	v_exp_f32_e32 v121, v123
	v_pk_add_f32 v[222:223], v[118:119], v[222:223]
	v_mfma_f32_32x32x16_bf16 v[16:31], v[166:169], v[88:91], v[16:31]
	v_exp_f32_e32 v122, v124
	v_exp_f32_e32 v123, v125
	v_pk_add_f32 v[222:223], v[120:121], v[222:223]
	v_mfma_f32_32x32x16_bf16 v[0:15], v[162:165], v[88:91], v[0:15]
	v_exp_f32_e32 v124, v126
	v_exp_f32_e32 v125, v127
	v_pk_add_f32 v[222:223], v[122:123], v[222:223]
	ds_read_b64_tr_b16 v[162:163], v221 offset:27648
	ds_read_b64_tr_b16 v[166:167], v221 offset:27712
	ds_read_b64_tr_b16 v[170:171], v221 offset:27776
	ds_read_b64_tr_b16 v[174:175], v221 offset:27840
	ds_read_b64_tr_b16 v[164:165], v221 offset:30208
	ds_read_b64_tr_b16 v[168:169], v221 offset:30272
	ds_read_b64_tr_b16 v[172:173], v221 offset:30336
	ds_read_b64_tr_b16 v[176:177], v221 offset:30400
	v_cvt_pk_bf16_f32 v116, v118, v119
	v_cvt_pk_bf16_f32 v117, v120, v121
	v_cvt_pk_bf16_f32 v118, v122, v123
	v_cvt_pk_bf16_f32 v119, v124, v125
	v_pk_add_f32 v[222:223], v[124:125], v[222:223]
	s_waitcnt lgkmcnt(11)
	v_mfma_f32_32x32x16_bf16 v[48:63], v[224:227], v[116:119], v[48:63]
	v_exp_f32_e32 v126, v96
	v_exp_f32_e32 v127, v97
	s_waitcnt lgkmcnt(10)
	v_mfma_f32_32x32x16_bf16 v[32:47], v[228:231], v[116:119], v[32:47]
	v_exp_f32_e32 v198, v98
	v_exp_f32_e32 v199, v99
	v_pk_add_f32 v[222:223], v[126:127], v[222:223]
	s_waitcnt lgkmcnt(9)
	v_mfma_f32_32x32x16_bf16 v[16:31], v[232:235], v[116:119], v[16:31]
	v_exp_f32_e32 v238, v100
	v_exp_f32_e32 v239, v101
	v_pk_add_f32 v[222:223], v[198:199], v[222:223]
	s_waitcnt lgkmcnt(8)
	v_mfma_f32_32x32x16_bf16 v[0:15], v[92:95], v[116:119], v[0:15]
	v_exp_f32_e32 v240, v102
	v_exp_f32_e32 v241, v103
	v_pk_add_f32 v[222:223], v[238:239], v[222:223]
	ds_read_b64_tr_b16 v[224:225], v221 offset:32768
	ds_read_b64_tr_b16 v[228:229], v221 offset:32832
	ds_read_b64_tr_b16 v[232:233], v221 offset:32896
	ds_read_b64_tr_b16 v[92:93], v221 offset:32960
	ds_read_b64_tr_b16 v[226:227], v221 offset:35328
	ds_read_b64_tr_b16 v[230:231], v221 offset:35392
	ds_read_b64_tr_b16 v[234:235], v221 offset:35456
	ds_read_b64_tr_b16 v[94:95], v221 offset:35520
	v_cvt_pk_bf16_f32 v116, v126, v127
	v_cvt_pk_bf16_f32 v117, v198, v199
	v_cvt_pk_bf16_f32 v118, v238, v239
	v_cvt_pk_bf16_f32 v119, v240, v241
	v_pk_add_f32 v[222:223], v[240:241], v[222:223]
	s_waitcnt lgkmcnt(11)
	v_mfma_f32_32x32x16_bf16 v[48:63], v[162:165], v[116:119], v[48:63]
	v_exp_f32_e32 v242, v104
	v_exp_f32_e32 v243, v105
	s_waitcnt lgkmcnt(10)
	v_mfma_f32_32x32x16_bf16 v[32:47], v[166:169], v[116:119], v[32:47]
	v_exp_f32_e32 v244, v106
	v_exp_f32_e32 v245, v107
	v_pk_add_f32 v[222:223], v[242:243], v[222:223]
	s_waitcnt lgkmcnt(9)
	v_mfma_f32_32x32x16_bf16 v[16:31], v[170:173], v[116:119], v[16:31]
	v_exp_f32_e32 v246, v108
	v_exp_f32_e32 v247, v109
	v_pk_add_f32 v[222:223], v[244:245], v[222:223]
	s_waitcnt lgkmcnt(8)
	v_mfma_f32_32x32x16_bf16 v[0:15], v[174:177], v[116:119], v[0:15]
	v_exp_f32_e32 v248, v110
	v_exp_f32_e32 v249, v111
	v_pk_add_f32 v[222:223], v[246:247], v[222:223]
	s_xor_b32 s1, s0, 1
	s_mul_i32 s1, s1, 0x9400
	v_add3_u32 v96, s1, v206, v207
	v_add_u32_e32 v98, s1, v128
	v_add3_u32 v97, s1, v208, v210
	v_add_u32_e32 v99, v98, v211
	v_add_u32_e32 v98, v98, v212
	v_cvt_pk_bf16_f32 v100, v242, v243
	v_cvt_pk_bf16_f32 v101, v244, v245
	v_cvt_pk_bf16_f32 v102, v246, v247
	v_cvt_pk_bf16_f32 v103, v248, v249
	v_pk_add_f32 v[222:223], v[248:249], v[222:223]
	s_nop 0
	v_add_f32_e32 v84, v222, v223
	s_waitcnt lgkmcnt(3)
	v_mfma_f32_32x32x16_bf16 v[48:63], v[224:227], v[100:103], v[48:63]
	v_add_f32_e32 v187, v187, v84
	s_waitcnt vmcnt(3)
	ds_write_b128 v96, v[146:149]
	s_waitcnt lgkmcnt(3)
	v_mfma_f32_32x32x16_bf16 v[32:47], v[228:231], v[100:103], v[32:47]
	s_waitcnt vmcnt(2)
	ds_write_b128 v97, v[150:153]
	s_waitcnt lgkmcnt(3)
	v_mfma_f32_32x32x16_bf16 v[16:31], v[232:235], v[100:103], v[16:31]
	s_waitcnt vmcnt(1)
	ds_write_b128 v99, v[154:157] offset:17408
	s_waitcnt lgkmcnt(3)
	v_mfma_f32_32x32x16_bf16 v[0:15], v[92:95], v[100:103], v[0:15]
	s_waitcnt vmcnt(0)
	ds_write_b128 v98, v[158:161] offset:17408
	s_setprio 0
	s_branch .Ltail2_d1
.LBB0_345:
	s_xor_b32 s0, s0, 1
	s_mul_i32 s0, s0, 0x9400
	s_add_i32 s0, s0, 0
	v_add3_u32 v96, s0, v206, v207
	v_add_u32_e32 v98, s0, v128
	v_add3_u32 v97, s0, v208, v210
	v_add_u32_e32 v99, v98, v211
	v_add_u32_e32 v98, v98, v212
	s_waitcnt vmcnt(3)
	ds_write_b128 v96, v[146:149]
	s_waitcnt vmcnt(2)
	ds_write_b128 v97, v[150:153]
	s_waitcnt vmcnt(1)
	ds_write_b128 v99, v[154:157] offset:17408
	s_waitcnt vmcnt(0)
	ds_write_b128 v98, v[158:161] offset:17408
.Ltail2_d1:
	s_add_i32 s45, s45, 1
	s_cmp_eq_u32 s31, s46
	s_waitcnt lgkmcnt(0)
	s_barrier
	s_cbranch_scc1 .LBB0_347
	s_mov_b32 s47, s46
	s_branch .LBB0_335

; #define LAS __attribute__((address_space(3)))
; template <bool DIFF> ...
;     ...
;             {
;                 bf16x8 kf[2][NS];
; #pragma unroll
;                 for (int kb = 0; kb < 2; ++kb)
; #pragma unroll
;                     for (int st = 0; st < NS; ++st) kf[kb][st] = *(const LAS bf16x8*)(kb_ + (kb * 32 + l32) * KROWB + (s * DQK + st * 16 + hi * 8) * 2);
;                 VLOAD(vfa, 0);
;                 __builtin_amdgcn_sched_barrier(0);
;                 __builtin_amdgcn_s_setprio(1);
; #pragma unroll
;                 for (int st = 0; st < NS; ++st) {
;                     pr[0] = __builtin_amdgcn_mfma_f32_32x32x16_bf16(kf[0][st], qf[st], st == 0 ? negm : pr[0], 0, 0, 0);
;                     pr[1] = __builtin_amdgcn_mfma_f32_32x32x16_bf16(kf[1][st], qf[st], st == 0 ? negm : pr[1], 0, 0, 0); }
;                 __builtin_amdgcn_s_setprio(0);
;             }
;             const int tp0 = (t == 0) ? -16 : (t - 1) * 64;
;             if (DIFF) {
;                 if (tp0 + 63 - qpos_w > -128) {
; #pragma unroll
;                     for (int kb = 0; kb < 2; ++kb)
; #pragma unroll
;                         for (int r = 0; r < 16; ++r) { const int kvi = kb * 32 + 8 * (r >> 2) + 4 * hi + (r & 3); int idx = tp0 + kvi - qpos + 128; idx = idx < 0 ? 0 : idx; pr[kb][r] += lut[idx]; }
;                 }
;             }
.LBB0_360:
	s_cmp_lt_u32 s26, s28
	s_mov_b64 s[0:1], -1
	s_cbranch_scc1 .LBB0_362
	s_add_i32 s20, s35, 64
	s_mov_b64 s[0:1], 0
.LBB0_362:
	s_andn2_b64 vcc, exec, s[0:1]
	s_and_b32 s0, s26, 1
	s_cbranch_vccnz .LBB0_367
	s_mul_i32 s1, s0, 0x9400
	s_add_i32 s1, s1, 0
	v_add_u32_e32 v96, s1, v213
	v_add3_u32 v97, s1, v215, v214
	v_add_u32_e32 v221, v96, v212
	ds_read_b128 v[80:83], v97
	ds_read_b128 v[84:87], v97 offset:32
	ds_read_b128 v[88:91], v97 offset:64
	ds_read_b128 v[92:95], v97 offset:96
	ds_read_b128 v[222:225], v97 offset:8704
	ds_read_b128 v[226:229], v97 offset:8736
	ds_read_b128 v[230:233], v97 offset:8768
	ds_read_b128 v[234:237], v97 offset:8800
	ds_read_b64_tr_b16 v[174:175], v221 offset:17408
	ds_read_b64_tr_b16 v[170:171], v221 offset:17472
	ds_read_b64_tr_b16 v[166:167], v221 offset:17536
	ds_read_b64_tr_b16 v[162:163], v221 offset:17600
	ds_read_b64_tr_b16 v[176:177], v221 offset:19968
	ds_read_b64_tr_b16 v[172:173], v221 offset:20032
	ds_read_b64_tr_b16 v[168:169], v221 offset:20096
	ds_read_b64_tr_b16 v[164:165], v221 offset:20160
	s_setprio 1
	s_waitcnt lgkmcnt(14)
	v_mfma_f32_32x32x16_bf16 v[112:127], v[80:83], v[142:145], v[64:79]
	s_waitcnt lgkmcnt(11)
	v_mfma_f32_32x32x16_bf16 v[96:111], v[222:225], v[142:145], v[64:79]
	v_add_u32_e32 v80, s35, v220
	v_ashrrev_i32_e32 v81, 31, v80
	v_add_u32_e32 v82, s35, v219
	v_lshlrev_b64 v[80:81], 11, v[80:81]
	v_mfma_f32_32x32x16_bf16 v[112:127], v[84:87], v[138:141], v[112:127]
	v_ashrrev_i32_e32 v83, 31, v82
	v_lshl_add_u64 v[80:81], v[190:191], 0, v[80:81]
	v_lshlrev_b64 v[82:83], 11, v[82:83]
	v_lshl_add_u64 v[82:83], v[192:193], 0, v[82:83]
	global_load_dwordx4 v[146:149], v[80:81], off
	global_load_dwordx4 v[150:153], v[82:83], off
	s_waitcnt lgkmcnt(10)
	v_mfma_f32_32x32x16_bf16 v[96:111], v[226:229], v[138:141], v[96:111]
	v_add_u32_e32 v80, s35, v218
	v_ashrrev_i32_e32 v81, 31, v80
	v_add_u32_e32 v82, s35, v217
	v_lshlrev_b64 v[80:81], 11, v[80:81]
	v_mfma_f32_32x32x16_bf16 v[112:127], v[88:91], v[134:137], v[112:127]
	v_ashrrev_i32_e32 v83, 31, v82
	v_lshl_add_u64 v[80:81], v[188:189], 0, v[80:81]
	v_lshlrev_b64 v[82:83], 11, v[82:83]
	v_lshl_add_u64 v[82:83], v[188:189], 0, v[82:83]
	global_load_dwordx4 v[154:157], v[80:81], off
	global_load_dwordx4 v[158:161], v[82:83], off
	s_waitcnt lgkmcnt(9)
	v_mfma_f32_32x32x16_bf16 v[96:111], v[230:233], v[134:137], v[96:111]
	v_mfma_f32_32x32x16_bf16 v[112:127], v[92:95], v[130:133], v[112:127]
	s_waitcnt lgkmcnt(8)
	v_mfma_f32_32x32x16_bf16 v[96:111], v[234:237], v[130:133], v[96:111]
	s_setprio 0
	s_add_i32 s20, s35, 64
	s_cmp_le_u32 s20, s30
	s_cbranch_scc1 .LBB0_365
	v_add_u32_e32 v200, s35, v216
	s_add_i32 s1, 0, 0x18000
	v_max_i32_e32 v222, 0xffffff5d, v200
	v_lshl_add_u32 v223, v222, 2, s1
	v_max_i32_e32 v222, 0xffffff58, v200
	v_max_i32_e32 v228, 0xffffff4f, v200
	v_lshl_add_u32 v224, v222, 2, s1
	v_max_i32_e32 v222, 0xffffff57, v200
	v_lshl_add_u32 v229, v228, 2, s1
	v_max_i32_e32 v228, 0xffffff4e, v200
	v_lshl_add_u32 v225, v222, 2, s1
	v_max_i32_e32 v222, 0xffffff56, v200
	v_lshl_add_u32 v230, v228, 2, s1
	v_max_i32_e32 v228, 0xffffff4d, v200
	v_max_i32_e32 v80, 0xffffff80, v200
	v_max_i32_e32 v81, 0xffffff7f, v200
	v_max_i32_e32 v82, 0xffffff7e, v200
	v_max_i32_e32 v83, 0xffffff7d, v200
	v_max_i32_e32 v84, 0xffffff78, v200
	v_max_i32_e32 v85, 0xffffff77, v200
	v_max_i32_e32 v86, 0xffffff76, v200
	v_max_i32_e32 v87, 0xffffff75, v200
	v_max_i32_e32 v88, 0xffffff70, v200
	v_max_i32_e32 v89, 0xffffff6f, v200
	v_max_i32_e32 v90, 0xffffff6e, v200
	v_max_i32_e32 v91, 0xffffff6d, v200
	v_max_i32_e32 v92, 0xffffff68, v200
	v_max_i32_e32 v93, 0xffffff67, v200
	v_max_i32_e32 v94, 0xffffff66, v200
	v_max_i32_e32 v95, 0xffffff65, v200
	v_max_i32_e32 v198, 0xffffff60, v200
	v_max_i32_e32 v199, 0xffffff5f, v200
	v_max_i32_e32 v201, 0xffffff5e, v200
	v_lshl_add_u32 v226, v222, 2, s1
	v_max_i32_e32 v222, 0xffffff55, v200
	v_lshl_add_u32 v231, v228, 2, s1
	v_max_i32_e32 v228, 0xffffff48, v200
	v_lshl_add_u32 v80, v80, 2, s1
	v_lshl_add_u32 v81, v81, 2, s1
	v_lshl_add_u32 v82, v82, 2, s1
	v_lshl_add_u32 v83, v83, 2, s1
	v_lshl_add_u32 v84, v84, 2, s1
	v_lshl_add_u32 v85, v85, 2, s1
	v_lshl_add_u32 v86, v86, 2, s1
	v_lshl_add_u32 v87, v87, 2, s1
	v_lshl_add_u32 v88, v88, 2, s1
	v_lshl_add_u32 v89, v89, 2, s1
	v_lshl_add_u32 v90, v90, 2, s1
	v_lshl_add_u32 v91, v91, 2, s1
	v_lshl_add_u32 v92, v92, 2, s1
	v_lshl_add_u32 v93, v93, 2, s1
	v_lshl_add_u32 v94, v94, 2, s1
	v_lshl_add_u32 v95, v95, 2, s1
	v_lshl_add_u32 v198, v198, 2, s1
	v_lshl_add_u32 v199, v199, 2, s1
	v_lshl_add_u32 v201, v201, 2, s1
	v_lshl_add_u32 v227, v222, 2, s1
	v_lshl_add_u32 v232, v228, 2, s1
	v_max_i32_e32 v228, 0xffffff47, v200
	ds_read_b32 v80, v80 offset:512
	ds_read_b32 v81, v81 offset:516
	ds_read_b32 v82, v82 offset:520
	ds_read_b32 v83, v83 offset:524
	ds_read_b32 v84, v84 offset:544
	ds_read_b32 v85, v85 offset:548
	ds_read_b32 v86, v86 offset:552
	ds_read_b32 v87, v87 offset:556
	ds_read_b32 v88, v88 offset:576
	ds_read_b32 v89, v89 offset:580
	ds_read_b32 v90, v90 offset:584
	ds_read_b32 v91, v91 offset:588
	ds_read_b32 v92, v92 offset:608
	ds_read_b32 v93, v93 offset:612
	ds_read_b32 v94, v94 offset:616
	ds_read_b32 v95, v95 offset:620
	ds_read_b32 v198, v198 offset:640
	ds_read_b32 v199, v199 offset:644
	ds_read_b32 v222, v201 offset:648
	ds_read_b32 v223, v223 offset:652
	ds_read_b32 v224, v224 offset:672
	ds_read_b32 v225, v225 offset:676
	ds_read_b32 v226, v226 offset:680
	ds_read_b32 v227, v227 offset:684
	v_max_i32_e32 v201, 0xffffff50, v200
	v_lshl_add_u32 v233, v228, 2, s1
	v_max_i32_e32 v228, 0xffffff46, v200
	v_lshl_add_u32 v201, v201, 2, s1
	v_lshl_add_u32 v234, v228, 2, s1
	v_max_i32_e32 v200, 0xffffff45, v200
	v_lshl_add_u32 v200, v200, 2, s1
	ds_read_b32 v228, v201 offset:704
	ds_read_b32 v229, v229 offset:708
	ds_read_b32 v230, v230 offset:712
	ds_read_b32 v231, v231 offset:716
	ds_read_b32 v232, v232 offset:736
	ds_read_b32 v233, v233 offset:740
	ds_read_b32 v234, v234 offset:744
	ds_read_b32 v235, v200 offset:748
	s_waitcnt lgkmcnt(14)
	v_pk_add_f32 v[126:127], v[126:127], v[94:95]
	v_pk_add_f32 v[124:125], v[124:125], v[92:93]
	v_pk_add_f32 v[122:123], v[122:123], v[90:91]
	v_pk_add_f32 v[120:121], v[120:121], v[88:89]
	v_pk_add_f32 v[118:119], v[118:119], v[86:87]
	v_pk_add_f32 v[116:117], v[116:117], v[84:85]
	v_pk_add_f32 v[114:115], v[114:115], v[82:83]
	v_pk_add_f32 v[112:113], v[112:113], v[80:81]
	s_waitcnt lgkmcnt(0)
	v_pk_add_f32 v[110:111], v[110:111], v[234:235]
	v_pk_add_f32 v[108:109], v[108:109], v[232:233]
	v_pk_add_f32 v[106:107], v[106:107], v[230:231]
	v_pk_add_f32 v[104:105], v[104:105], v[228:229]
	v_pk_add_f32 v[102:103], v[102:103], v[226:227]
	v_pk_add_f32 v[100:101], v[100:101], v[224:225]
	v_pk_add_f32 v[98:99], v[98:99], v[222:223]
	v_pk_add_f32 v[96:97], v[96:97], v[198:199]

; template <bool DIFF> ...
;     ...
;             f32x2 ps2 = (f32x2){0.f, 0.f};
; #pragma unroll
;             for (int kb = 0; kb < 2; ++kb)
; #pragma unroll
;                 for (int r = 0; r < 16; r += 2) { const float e0 = __builtin_amdgcn_exp2f(pr[kb][r]), e1 = __builtin_amdgcn_exp2f(pr[kb][r + 1]); pr[kb][r] = e0; pr[kb][r + 1] = e1; ps2 += (f32x2){e0, e1}; }
;             lsum += ps2[0] + ps2[1];
;             __builtin_amdgcn_sched_barrier(0);
;             VLOAD(vfb, 1); __builtin_amdgcn_sched_barrier(0); PVMMA(vfa, 0); __builtin_amdgcn_sched_barrier(0);
;             VLOAD(vfa, 2); __builtin_amdgcn_sched_barrier(0); PVMMA(vfb, 1); __builtin_amdgcn_sched_barrier(0);
;             VLOAD(vfb, 3); __builtin_amdgcn_sched_barrier(0); PVMMA(vfa, 2); __builtin_amdgcn_sched_barrier(0);
;             PVMMA(vfb, 3);
;     ...
;         }
;         if (t + 1 < NT) ATT_LSTORE(buf ^ 1);
;         __syncthreads();
.LBB0_367:
	v_add_u32_e32 v80, s35, v220
	v_ashrrev_i32_e32 v81, 31, v80
	v_add_u32_e32 v82, s35, v219
	v_lshlrev_b64 v[80:81], 11, v[80:81]
	v_ashrrev_i32_e32 v83, 31, v82
	v_lshl_add_u64 v[80:81], v[190:191], 0, v[80:81]
	v_lshlrev_b64 v[82:83], 11, v[82:83]
	v_lshl_add_u64 v[82:83], v[192:193], 0, v[82:83]
	global_load_dwordx4 v[146:149], v[80:81], off
	global_load_dwordx4 v[150:153], v[82:83], off
	v_add_u32_e32 v80, s35, v218
	v_ashrrev_i32_e32 v81, 31, v80
	v_add_u32_e32 v82, s35, v217
	v_lshlrev_b64 v[80:81], 11, v[80:81]
	v_ashrrev_i32_e32 v83, 31, v82
	v_lshl_add_u64 v[80:81], v[188:189], 0, v[80:81]
	v_lshlrev_b64 v[82:83], 11, v[82:83]
	v_lshl_add_u64 v[82:83], v[188:189], 0, v[82:83]
	global_load_dwordx4 v[154:157], v[80:81], off
	global_load_dwordx4 v[158:161], v[82:83], off
	s_branch .LBB0_370
.LBB0_368:
.LBB0_369:
	ds_read_b64_tr_b16 v[224:225], v221 offset:22528
	ds_read_b64_tr_b16 v[228:229], v221 offset:22592
	ds_read_b64_tr_b16 v[232:233], v221 offset:22656
	ds_read_b64_tr_b16 v[92:93], v221 offset:22720
	ds_read_b64_tr_b16 v[226:227], v221 offset:25088
	ds_read_b64_tr_b16 v[230:231], v221 offset:25152
	ds_read_b64_tr_b16 v[234:235], v221 offset:25216
	ds_read_b64_tr_b16 v[94:95], v221 offset:25280
	v_exp_f32_e32 v236, v112
	v_exp_f32_e32 v237, v113
	v_exp_f32_e32 v112, v114
	v_exp_f32_e32 v113, v115
	v_pk_add_f32 v[222:223], v[236:237], 0 op_sel_hi:[1,0]
	v_exp_f32_e32 v114, v116
	v_exp_f32_e32 v115, v117
	v_pk_add_f32 v[222:223], v[112:113], v[222:223]
	v_exp_f32_e32 v116, v118
	v_exp_f32_e32 v117, v119
	v_pk_add_f32 v[222:223], v[114:115], v[222:223]
	v_cvt_pk_bf16_f32 v88, v236, v237
	v_cvt_pk_bf16_f32 v89, v112, v113
	v_cvt_pk_bf16_f32 v90, v114, v115
	v_cvt_pk_bf16_f32 v91, v116, v117
	s_setprio 1
	v_pk_add_f32 v[222:223], v[116:117], v[222:223]
	s_waitcnt lgkmcnt(8)
	v_mfma_f32_32x32x16_bf16 v[48:63], v[174:177], v[88:91], v[48:63]
	v_exp_f32_e32 v118, v120
	v_exp_f32_e32 v119, v121
	v_mfma_f32_32x32x16_bf16 v[32:47], v[170:173], v[88:91], v[32:47]
	v_exp_f32_e32 v120, v122
	v_exp_f32_e32 v121, v123
	v_pk_add_f32 v[222:223], v[118:119], v[222:223]
	v_mfma_f32_32x32x16_bf16 v[16:31], v[166:169], v[88:91], v[16:31]
	v_exp_f32_e32 v122, v124
	v_exp_f32_e32 v123, v125
	v_pk_add_f32 v[222:223], v[120:121], v[222:223]
	v_mfma_f32_32x32x16_bf16 v[0:15], v[162:165], v[88:91], v[0:15]
	v_exp_f32_e32 v124, v126
	v_exp_f32_e32 v125, v127
	v_pk_add_f32 v[222:223], v[122:123], v[222:223]
	ds_read_b64_tr_b16 v[162:163], v221 offset:27648
	ds_read_b64_tr_b16 v[166:167], v221 offset:27712
	ds_read_b64_tr_b16 v[170:171], v221 offset:27776
	ds_read_b64_tr_b16 v[174:175], v221 offset:27840
	ds_read_b64_tr_b16 v[164:165], v221 offset:30208
	ds_read_b64_tr_b16 v[168:169], v221 offset:30272
	ds_read_b64_tr_b16 v[172:173], v221 offset:30336
	ds_read_b64_tr_b16 v[176:177], v221 offset:30400
	v_cvt_pk_bf16_f32 v116, v118, v119
	v_cvt_pk_bf16_f32 v117, v120, v121
	v_cvt_pk_bf16_f32 v118, v122, v123
	v_cvt_pk_bf16_f32 v119, v124, v125
	v_pk_add_f32 v[222:223], v[124:125], v[222:223]
	s_waitcnt lgkmcnt(11)
	v_mfma_f32_32x32x16_bf16 v[48:63], v[224:227], v[116:119], v[48:63]
	v_exp_f32_e32 v126, v96
	v_exp_f32_e32 v127, v97
	s_waitcnt lgkmcnt(10)
	v_mfma_f32_32x32x16_bf16 v[32:47], v[228:231], v[116:119], v[32:47]
	v_exp_f32_e32 v198, v98
	v_exp_f32_e32 v199, v99
	v_pk_add_f32 v[222:223], v[126:127], v[222:223]
	s_waitcnt lgkmcnt(9)
	v_mfma_f32_32x32x16_bf16 v[16:31], v[232:235], v[116:119], v[16:31]
	v_exp_f32_e32 v238, v100
	v_exp_f32_e32 v239, v101
	v_pk_add_f32 v[222:223], v[198:199], v[222:223]
	s_waitcnt lgkmcnt(8)
	v_mfma_f32_32x32x16_bf16 v[0:15], v[92:95], v[116:119], v[0:15]
	v_exp_f32_e32 v240, v102
	v_exp_f32_e32 v241, v103
	v_pk_add_f32 v[222:223], v[238:239], v[222:223]
	ds_read_b64_tr_b16 v[224:225], v221 offset:32768
	ds_read_b64_tr_b16 v[228:229], v221 offset:32832
	ds_read_b64_tr_b16 v[232:233], v221 offset:32896
	ds_read_b64_tr_b16 v[92:93], v221 offset:32960
	ds_read_b64_tr_b16 v[226:227], v221 offset:35328
	ds_read_b64_tr_b16 v[230:231], v221 offset:35392
	ds_read_b64_tr_b16 v[234:235], v221 offset:35456
	ds_read_b64_tr_b16 v[94:95], v221 offset:35520
	v_cvt_pk_bf16_f32 v116, v126, v127
	v_cvt_pk_bf16_f32 v117, v198, v199
	v_cvt_pk_bf16_f32 v118, v238, v239
	v_cvt_pk_bf16_f32 v119, v240, v241
	v_pk_add_f32 v[222:223], v[240:241], v[222:223]
	s_waitcnt lgkmcnt(11)
	v_mfma_f32_32x32x16_bf16 v[48:63], v[162:165], v[116:119], v[48:63]
	v_exp_f32_e32 v242, v104
	v_exp_f32_e32 v243, v105
	s_waitcnt lgkmcnt(10)
	v_mfma_f32_32x32x16_bf16 v[32:47], v[166:169], v[116:119], v[32:47]
	v_exp_f32_e32 v244, v106
	v_exp_f32_e32 v245, v107
	v_pk_add_f32 v[222:223], v[242:243], v[222:223]
	s_waitcnt lgkmcnt(9)
	v_mfma_f32_32x32x16_bf16 v[16:31], v[170:173], v[116:119], v[16:31]
	v_exp_f32_e32 v246, v108
	v_exp_f32_e32 v247, v109
	v_pk_add_f32 v[222:223], v[244:245], v[222:223]
	s_waitcnt lgkmcnt(8)
	v_mfma_f32_32x32x16_bf16 v[0:15], v[174:177], v[116:119], v[0:15]
	v_exp_f32_e32 v248, v110
	v_exp_f32_e32 v249, v111
	v_pk_add_f32 v[222:223], v[246:247], v[222:223]
	s_xor_b32 s1, s0, 1
	s_mul_i32 s1, s1, 0x9400
	v_add3_u32 v96, s1, v206, v207
	v_add_u32_e32 v98, s1, v128
	v_add3_u32 v97, s1, v208, v209
	v_add_u32_e32 v99, v98, v210
	v_add_u32_e32 v98, v98, v211
	v_cvt_pk_bf16_f32 v100, v242, v243
	v_cvt_pk_bf16_f32 v101, v244, v245
	v_cvt_pk_bf16_f32 v102, v246, v247
	v_cvt_pk_bf16_f32 v103, v248, v249
	v_pk_add_f32 v[222:223], v[248:249], v[222:223]
	s_nop 0
	v_add_f32_e32 v84, v222, v223
	s_waitcnt lgkmcnt(3)
	v_mfma_f32_32x32x16_bf16 v[48:63], v[224:227], v[100:103], v[48:63]
	v_add_f32_e32 v187, v187, v84
	s_waitcnt vmcnt(3)
	ds_write_b128 v96, v[146:149]
	s_waitcnt lgkmcnt(3)
	v_mfma_f32_32x32x16_bf16 v[32:47], v[228:231], v[100:103], v[32:47]
	s_waitcnt vmcnt(2)
	ds_write_b128 v97, v[150:153]
	s_waitcnt lgkmcnt(3)
	v_mfma_f32_32x32x16_bf16 v[16:31], v[232:235], v[100:103], v[16:31]
	s_waitcnt vmcnt(1)
	ds_write_b128 v99, v[154:157] offset:17408
	s_waitcnt lgkmcnt(3)
	v_mfma_f32_32x32x16_bf16 v[0:15], v[92:95], v[100:103], v[0:15]
	s_waitcnt vmcnt(0)
	ds_write_b128 v98, v[158:161] offset:17408
	s_setprio 0
	s_branch .Ltail2_d2
.LBB0_370:
	s_xor_b32 s0, s0, 1
	s_mul_i32 s0, s0, 0x9400
	s_add_i32 s0, s0, 0
	v_add3_u32 v96, s0, v206, v207
	v_add_u32_e32 v98, s0, v128
	v_add3_u32 v97, s0, v208, v209
	v_add_u32_e32 v99, v98, v210
	v_add_u32_e32 v98, v98, v211
	s_waitcnt vmcnt(3)
	ds_write_b128 v96, v[146:149]
	s_waitcnt vmcnt(2)
	ds_write_b128 v97, v[150:153]
	s_waitcnt vmcnt(1)
	ds_write_b128 v99, v[154:157] offset:17408
	s_waitcnt vmcnt(0)
	ds_write_b128 v98, v[158:161] offset:17408
.Ltail2_d2:
	s_add_i32 s26, s26, 1
	s_cmp_eq_u32 s31, s20
	s_waitcnt lgkmcnt(0)
	s_barrier
	s_cbranch_scc1 .LBB0_372
	s_mov_b32 s35, s20
	s_branch .LBB0_360

; #define LAS __attribute__((address_space(3)))
; __device__ __forceinline__ int tid_fresh() { int t = threadIdx.x; asm volatile("" : "+v"(t)); return t; }
; template <bool DIFF> ...
;     ...
;     const int tid = tid_fresh(), lane = tid & 63, wid = __builtin_amdgcn_readfirstlane(tid >> 6), s = wid >> 2, l32 = lane & 31, hi = lane >> 5;
;     const int kcol0 = hx * (2 * DQK), vcol0 = hx * 128, sdv = DIFF ? 0 : s * 64;
;     LAS float* lut = (LAS float*)(lds + LUT_OFF);
;     u32x4 kst[NKC], vst[2];
;     ...
;     ATT_GLOAD(0);
;     if (DIFF) { if (tid < 192) lut[tid] = lutg[hx * 192 + tid] - lutg[hx * 192]; }
;     bf16x8 qf[NS];
;     { const int qi = l32 < nqv ? l32 : (nqv > 0 ? nqv - 1 : 0);
;       const bf16_t* qp = Qg + (size_t)(qrow_w + qi) * KP + (DIFF ? hx * 128 + s * 64 : (hx * 2 + s) * 96) + hi * 8;
; #pragma unroll
;       for (int st = 0; st < NS; ++st) qf[st] = *(const bf16x8*)(qp + st * 16); }
;     f32x16 o[NDB];
; #pragma unroll
;     for (int db = 0; db < NDB; ++db)
; #pragma unroll
;         for (int r = 0; r < 16; ++r) o[db][r] = 0.f;
;     float mrun = 0.f, lsum = 0.f; f32x16 negm;
; #pragma unroll
;     for (int r = 0; r < 16; ++r) negm[r] = 0.f;
;     ATT_LSTORE(0);
;     __syncthreads();
.LBB0_694:
	s_lshl_b32 s0, s44, 6
	s_and_b32 s0, s0, 0x780
	s_or_b32 s25, s0, 64
	s_ashr_i32 s0, s30, 31
	s_lshr_b32 s0, s0, 26
	s_add_i32 s0, s30, s0
	s_ashr_i32 s16, s0, 6
	s_ashr_i32 s0, s30, 4
	s_lshr_b32 s1, s0, 30
	s_add_i32 s1, s0, s1
	s_and_b32 s1, s1, -4
	v_mov_b32_e32 v0, v194
	s_sub_i32 s24, s0, s1
	s_load_dwordx2 s[26:27], s[42:43], 0xd8
	s_lshl_b32 s1, s30, 1
	v_readfirstlane_b32 s0, v0
	s_and_b32 s17, s1, 30
	s_bfe_u32 s1, s0, 0x10007
	s_or_b32 s35, s1, s17
	s_lshr_b32 s0, s0, 1
	s_lshl_b32 s1, s35, 6
	s_and_b32 s0, s0, 32
	s_or_b32 s0, s1, s0
	s_lshl_b32 s20, s16, 12
	v_mov_b32_e32 v20, v194
	s_or_b32 s38, s0, s20
	s_add_i32 s35, s35, 2
	s_waitcnt lgkmcnt(0)
	s_add_u32 s18, s26, 0x38148000
	v_mul_hi_i32 v0, v20, s46
	s_mul_i32 s0, s24, 0xc0
	v_lshrrev_b32_e32 v1, 31, v0
	v_ashrrev_i32_e32 v0, 2, v0
	s_addc_u32 s19, s27, 0
	s_ashr_i32 s1, s0, 31
	v_add_u32_e32 v85, v0, v1
	s_lshl_b32 s22, s24, 7
	s_lshl_b64 s[0:1], s[0:1], 1
	v_mad_u64_u32 v[22:23], s[28:29], v85, s47, v[20:21]
	s_add_u32 s0, s26, s0
	v_lshlrev_b32_e32 v2, 3, v22
	v_add_u32_e32 v8, 0x400, v20
	s_addc_u32 s1, s27, s1
	v_ashrrev_i32_e32 v3, 31, v2
	v_add_u32_e32 v16, 0x200, v20
	v_mul_hi_i32 v9, v8, s46
	s_add_u32 s0, s0, 0x3b1a8000
	v_lshlrev_b64 v[54:55], 1, v[2:3]
	v_mul_hi_i32 v2, v16, s46
	v_lshrrev_b32_e32 v10, 31, v9
	v_ashrrev_i32_e32 v9, 2, v9
	s_addc_u32 s1, s1, 0
	v_lshrrev_b32_e32 v3, 31, v2
	v_ashrrev_i32_e32 v2, 2, v2
	v_add_u32_e32 v89, v9, v10
	s_ashr_i32 s23, s22, 31
	v_add_u32_e32 v88, v2, v3
	v_mad_u64_u32 v[28:29], s[28:29], v89, s47, v[8:9]
	s_lshl_b64 s[22:23], s[22:23], 1
	v_add_u32_e32 v0, 0xa600, v85
	v_mov_b64_e32 v[24:25], s[0:1]
	v_add_u32_e32 v2, 0xa600, v88
	v_add_u32_e32 v8, 0xa600, v89
	v_lshlrev_b32_e32 v10, 3, v28
	s_add_u32 s22, s26, s22
	v_mad_i64_i32 v[0:1], s[28:29], v0, s2, v[24:25]
	v_mad_u64_u32 v[26:27], s[28:29], v88, s47, v[16:17]
	v_mad_i64_i32 v[2:3], s[28:29], v2, s2, v[24:25]
	v_mad_i64_i32 v[8:9], s[28:29], v8, s2, v[24:25]
	v_ashrrev_i32_e32 v11, 31, v10
	s_addc_u32 s23, s27, s23
	v_lshlrev_b64 v[58:59], 1, v[10:11]
	s_add_u32 s28, s22, 0.5
	v_lshlrev_b32_e32 v10, 4, v20
	v_ashrrev_i32_e32 v60, 4, v20
	s_addc_u32 s29, s23, 0
	v_and_b32_e32 v128, 0xf0, v10
	v_ashrrev_i32_e32 v61, 31, v60
	v_lshl_add_u64 v[154:155], s[28:29], 0, v[128:129]
	v_lshlrev_b64 v[10:11], 10, v[60:61]
	v_ashrrev_i32_e32 v62, 4, v16
	v_lshlrev_b32_e32 v4, 3, v26
	v_lshl_add_u64 v[10:11], v[154:155], 0, v[10:11]
	v_ashrrev_i32_e32 v63, 31, v62
	v_ashrrev_i32_e32 v5, 31, v4
	v_add_co_u32_e32 v12, vcc, s48, v10
	v_lshlrev_b64 v[16:17], 10, v[62:63]
	v_lshlrev_b64 v[56:57], 1, v[4:5]
	v_addc_co_u32_e32 v13, vcc, 0, v11, vcc
	v_lshl_add_u64 v[16:17], v[154:155], 0, v[16:17]
	v_lshl_add_u64 v[0:1], v[0:1], 0, v[54:55]
	v_lshl_add_u64 v[4:5], v[2:3], 0, v[56:57]
	v_add_co_u32_e32 v16, vcc, s48, v16
	global_load_dwordx4 v[0:3], v[0:1], off
	s_nop 0
	global_load_dwordx4 v[4:7], v[4:5], off
	v_lshl_add_u64 v[8:9], v[8:9], 0, v[58:59]
	v_addc_co_u32_e32 v17, vcc, 0, v17, vcc
	global_load_dwordx4 v[8:11], v[8:9], off
	s_nop 0
	global_load_dwordx4 v[12:15], v[12:13], off
	v_and_b32_e32 v21, 31, v20
	global_load_dwordx4 v[16:19], v[16:17], off
	v_readfirstlane_b32 s22, v20
	v_or_b32_e32 v150, s38, v21
	v_mov_b64_e32 v[30:31], s[18:19]
	s_ashr_i32 s40, s22, 8
	v_mad_i64_i32 v[30:31], s[22:23], v150, s2, v[30:31]
	s_lshl_b32 s23, s24, 1
	s_add_i32 s24, s40, s23
	s_mul_i32 s38, s24, 0x60
	v_bfe_u32 v23, v20, 5, 1
	s_ashr_i32 s39, s38, 31
	v_lshl_add_u64 v[30:31], s[38:39], 1, v[30:31]
	s_waitcnt vmcnt(5)
	v_lshlrev_b32_e32 v32, 4, v23
	v_mov_b32_e32 v33, v129
	v_mul_lo_u32 v164, v85, s58
	v_lshlrev_b32_e32 v165, 4, v22
	v_lshl_add_u64 v[30:31], v[30:31], 0, v[32:33]
	v_add3_u32 v61, 0, v164, v165
	s_mulk_i32 s16, 0x1040
	global_load_dwordx4 v[116:119], v[30:31], off
	global_load_dwordx4 v[112:115], v[30:31], off offset:32
	global_load_dwordx4 v[108:111], v[30:31], off offset:64
	global_load_dwordx4 v[104:107], v[30:31], off offset:96
	global_load_dwordx4 v[100:103], v[30:31], off offset:128
	global_load_dwordx4 v[96:99], v[30:31], off offset:160
	v_mul_lo_u32 v166, v88, s58
	v_lshlrev_b32_e32 v167, 4, v26
	v_mul_lo_u32 v168, v89, s58
	v_lshlrev_b32_e32 v169, 4, v28
	v_mul_lo_u32 v170, v60, s75
	v_mul_lo_u32 v171, v62, s75
	v_add3_u32 v63, 0, v166, v167
	v_add3_u32 v90, 0, v168, v169
	s_add_i32 s22, s16, 64
	v_lshlrev_b32_e32 v162, 2, v23
	v_mul_u32_u24_e32 v175, 0x190, v21
	v_ashrrev_i32_e32 v151, 31, v150
	s_waitcnt vmcnt(10)
	ds_write_b128 v61, v[0:3]
	v_add_u32_e32 v0, 0, v128
	v_add_u32_e32 v1, v0, v170
	v_add_u32_e32 v0, v0, v171
	s_waitcnt vmcnt(9)
	ds_write_b128 v63, v[4:7]
	s_waitcnt vmcnt(8)
	ds_write_b128 v90, v[8:11]
	s_waitcnt vmcnt(7)
	ds_write_b128 v1, v[12:15] offset:25600
	s_waitcnt vmcnt(6)
	ds_write_b128 v0, v[16:19] offset:25600
	v_add_u32_e32 v0, s22, v85
	v_add_u32_e32 v2, s22, v88
	v_mad_i64_i32 v[0:1], s[38:39], v0, s2, v[24:25]
	v_mad_i64_i32 v[2:3], s[38:39], v2, s2, v[24:25]
	v_lshl_add_u64 v[0:1], v[0:1], 0, v[54:55]
	v_lshl_add_u64 v[2:3], v[2:3], 0, v[56:57]
	s_waitcnt lgkmcnt(0)
	s_barrier
; #define LAS __attribute__((address_space(3)))
; template <bool DIFF> ...
;     ...
;     for (int t = 0; t < NT; ++t) {
;         const int buf = t & 1;
;         if (t + 1 < NT) ATT_GLOAD(t + 1);
;         if (t < nt_w) {
;             const LAS unsigned char* kb_ = lds + buf * BUFB; const LAS unsigned char* vb_ = kb_ + KTILEB;
;             f32x16 pr[2];
;             const LAS unsigned char* vbase = vb_ + (4 * hi + ((lane & 15) >> 2)) * VROWB + (sdv + ((lane >> 4) & 1) * 16 + (lane & 3) * 4) * 2;
;     ...
;             bf16x8 vfa[NDB], vfb[NDB];
;             {
;                 bf16x8 kf[2][NS];
; #pragma unroll
;                 for (int kb = 0; kb < 2; ++kb)
; #pragma unroll
;                     for (int st = 0; st < NS; ++st) kf[kb][st] = *(const LAS bf16x8*)(kb_ + (kb * 32 + l32) * KROWB + (s * DQK + st * 16 + hi * 8) * 2);
;                 VLOAD(vfa, 0);
;                 __builtin_amdgcn_sched_barrier(0);
;                 __builtin_amdgcn_s_setprio(1);
; #pragma unroll
;                 for (int st = 0; st < NS; ++st) {
;                     pr[0] = __builtin_amdgcn_mfma_f32_32x32x16_bf16(kf[0][st], qf[st], st == 0 ? negm : pr[0], 0, 0, 0);
;                     pr[1] = __builtin_amdgcn_mfma_f32_32x32x16_bf16(kf[1][st], qf[st], st == 0 ? negm : pr[1], 0, 0, 0); }
;                 __builtin_amdgcn_s_setprio(0);
;             }
;             const int tp0 = (t == 0) ? -16 : (t - 1) * 64;
;             if (DIFF) {
;                 if (tp0 + 63 - qpos_w > -128) {
; #pragma unroll
;                     for (int kb = 0; kb < 2; ++kb)
; #pragma unroll
;                         for (int r = 0; r < 16; ++r) { const int kvi = kb * 32 + 8 * (r >> 2) + 4 * hi + (r & 3); int idx = tp0 + kvi - qpos + 128; idx = idx < 0 ? 0 : idx; pr[kb][r] += lut[idx]; }
;                 }
;             }
;             const int nval = (t == 0) ? 16 : (t == NT - 1 ? lastv : 64);
;             if (nval < 64) {
; #pragma unroll
;                 for (int kb = 0; kb < 2; ++kb)
; #pragma unroll
;                     for (int r = 0; r < 16; ++r) { const int kvi = kb * 32 + 8 * (r >> 2) + 4 * hi + (r & 3); if (kvi >= nval) pr[kb][r] = -INFINITY; }
;             }
;             float mx;
;             { float a0 = fmaxf(fmaxf(pr[0][0], pr[0][1]), pr[0][2]), a1 = fmaxf(fmaxf(pr[1][0], pr[1][1]), pr[1][2]);
; #pragma unroll
	global_load_dwordx4 v[34:37], v[0:1], off
	global_load_dwordx4 v[38:41], v[2:3], off
	v_add_u32_e32 v0, s22, v89
	v_add_u32_e32 v2, s22, v60
	v_mad_i64_i32 v[0:1], s[38:39], v0, s2, v[24:25]
	v_ashrrev_i32_e32 v3, 31, v2
	v_lshl_add_u64 v[0:1], v[0:1], 0, v[58:59]
	v_lshlrev_b64 v[2:3], 10, v[2:3]
	v_lshl_add_u64 v[2:3], v[154:155], 0, v[2:3]
	global_load_dwordx4 v[46:49], v[0:1], off
	global_load_dwordx4 v[42:45], v[2:3], off
	v_add_u32_e32 v0, s22, v62
	v_ashrrev_i32_e32 v1, 31, v0
	v_lshlrev_b64 v[0:1], 10, v[0:1]
	v_lshl_add_u64 v[0:1], v[154:155], 0, v[0:1]
	global_load_dwordx4 v[50:53], v[0:1], off
	v_lshrrev_b32_e32 v0, 2, v20
	s_lshl_b32 s39, s40, 6
	v_and_or_b32 v0, v0, 3, v162
	v_lshlrev_b32_e32 v1, 2, v20
	s_mulk_i32 s40, 0xc0
	v_mul_u32_u24_e32 v173, 0x140, v0
	v_and_b32_e32 v0, 16, v20
	v_and_b32_e32 v1, 12, v1
	v_or_b32_e32 v174, s40, v32
	v_or3_b32 v0, s39, v0, v1
	v_add3_u32 v5, 0, v175, v174
	v_and_b32_e32 v4, 63, v20
	v_lshlrev_b32_e32 v172, 1, v0
	ds_read_b128 v[0:3], v5
	ds_read_b128 v[16:19], v5 offset:32
	ds_read_b128 v[20:23], v5 offset:64
	ds_read_b128 v[24:27], v5 offset:96
	ds_read_b128 v[28:31], v5 offset:128
	ds_read_b128 v[64:67], v5 offset:160
	v_add3_u32 v33, 0, v173, v172
	ds_read_b64_tr_b16 v[68:69], v33 offset:25600
	ds_read_b64_tr_b16 v[70:71], v33 offset:28160
	ds_read_b64_tr_b16 v[74:75], v33 offset:28224
	ds_read_b64_tr_b16 v[72:73], v33 offset:25664
	v_lshlrev_b32_e32 v4, 2, v4
	s_mov_b32 s38, 1
	s_mov_b32 s39, 0
	v_xor_b32_e32 v163, 0x80, v4
	s_setprio 1
	s_waitcnt vmcnt(10) lgkmcnt(9)
	v_mfma_f32_32x32x16_bf16 v[0:15], v[0:3], v[116:119], 0
	s_waitcnt vmcnt(9) lgkmcnt(8)
	v_mfma_f32_32x32x16_bf16 v[0:15], v[16:19], v[112:115], v[0:15]
	s_waitcnt vmcnt(8) lgkmcnt(7)
	v_mfma_f32_32x32x16_bf16 v[0:15], v[20:23], v[108:111], v[0:15]
	s_waitcnt vmcnt(7) lgkmcnt(6)
	v_mfma_f32_32x32x16_bf16 v[0:15], v[24:27], v[104:107], v[0:15]
	s_waitcnt vmcnt(6) lgkmcnt(5)
	v_mfma_f32_32x32x16_bf16 v[0:15], v[28:31], v[100:103], v[0:15]
	s_waitcnt vmcnt(5) lgkmcnt(4)
	v_mfma_f32_32x32x16_bf16 v[0:15], v[64:67], v[96:99], v[0:15]
	s_setprio 0
	s_nop 10
	v_max3_f32 v8, v0, v1, v2
	v_max3_f32 v8, v8, v3, v4
	v_max3_f32 v8, v8, v5, v6
	s_mov_b32 s40, 0xff800000
	v_max3_f32 v8, v8, v7, s40
	ds_bpermute_b32 v9, v163, v8
	s_waitcnt lgkmcnt(0)
	v_max_f32_e32 v9, v9, v9
	v_max_f32_e32 v32, v8, v9
	v_sub_f32_e32 v1, v1, v32
	v_sub_f32_e32 v0, v0, v32
	v_sub_f32_e32 v9, v7, v32
	v_sub_f32_e32 v8, v6, v32
	v_sub_f32_e32 v7, v5, v32
	v_sub_f32_e32 v6, v4, v32
	v_sub_f32_e32 v5, v3, v32
	v_sub_f32_e32 v4, v2, v32
	v_exp_f32_e32 v0, v0
	v_exp_f32_e32 v1, v1
	v_exp_f32_e32 v4, v4
	v_exp_f32_e32 v5, v5
	v_exp_f32_e32 v6, v6
	v_exp_f32_e32 v7, v7
	v_sub_f32_e32 v10, 0xff800000, v32
	v_exp_f32_e32 v8, v8
	v_exp_f32_e32 v9, v9
	v_pk_add_f32 v[2:3], v[0:1], 0 op_sel_hi:[1,0]
	v_exp_f32_e32 v84, v10
	v_pk_add_f32 v[2:3], v[4:5], v[2:3]
	s_nop 0
	v_pk_add_f32 v[2:3], v[6:7], v[2:3]
	s_nop 0
	v_pk_add_f32 v[2:3], v[8:9], v[2:3]
	s_nop 0
	v_pk_add_f32 v[2:3], v[84:85], v[2:3] op_sel_hi:[0,1]
	v_pk_add_f32 v[2:3], v[84:85], v[2:3] op_sel_hi:[0,1]
	v_pk_add_f32 v[2:3], v[84:85], v[2:3] op_sel_hi:[0,1]
	v_pk_add_f32 v[2:3], v[84:85], v[2:3] op_sel_hi:[0,1]
	v_pk_add_f32 v[2:3], v[84:85], v[2:3] op_sel_hi:[0,1]
	v_pk_add_f32 v[2:3], v[84:85], v[2:3] op_sel_hi:[0,1]
	v_pk_add_f32 v[2:3], v[84:85], v[2:3] op_sel_hi:[0,1]
	v_pk_add_f32 v[2:3], v[84:85], v[2:3] op_sel_hi:[0,1]
	v_pk_add_f32 v[2:3], v[84:85], v[2:3] op_sel_hi:[0,1]
	v_pk_add_f32 v[2:3], v[84:85], v[2:3] op_sel_hi:[0,1]
	v_pk_add_f32 v[2:3], v[84:85], v[2:3] op_sel_hi:[0,1]
	v_pk_add_f32 v[2:3], v[84:85], v[2:3] op_sel_hi:[0,1]
	v_pk_add_f32 v[86:87], v[2:3], v[2:3] op_sel_hi:[0,1]
	ds_read_b64_tr_b16 v[64:65], v33 offset:30720
	ds_read_b64_tr_b16 v[66:67], v33 offset:33280
	ds_read_b64_tr_b16 v[76:77], v33 offset:30784
	ds_read_b64_tr_b16 v[78:79], v33 offset:33344
	v_cvt_pk_bf16_f32 v0, v0, v1
	v_cvt_pk_bf16_f32 v1, v4, v5
	v_cvt_pk_bf16_f32 v2, v6, v7
	v_cvt_pk_bf16_f32 v3, v8, v9
	s_setprio 1
	v_mfma_f32_32x32x16_bf16 v[16:31], v[68:71], v[0:3], 0
	v_mfma_f32_32x32x16_bf16 v[0:15], v[72:75], v[0:3], 0
	s_setprio 0
	ds_read_b64_tr_b16 v[68:69], v33 offset:35840
	ds_read_b64_tr_b16 v[70:71], v33 offset:38400
	ds_read_b64_tr_b16 v[74:75], v33 offset:38464
	ds_read_b64_tr_b16 v[72:73], v33 offset:35904
	v_cvt_pk_bf16_f32 v80, v84, v84
	v_cvt_pk_bf16_f32 v81, v84, v84
	v_cvt_pk_bf16_f32 v82, v84, v84
	v_cvt_pk_bf16_f32 v83, v84, v84
	s_setprio 1
	s_waitcnt lgkmcnt(6)
	v_mfma_f32_32x32x16_bf16 v[16:31], v[64:67], v[80:83], v[16:31]
	s_waitcnt lgkmcnt(4)
	v_mfma_f32_32x32x16_bf16 v[0:15], v[76:79], v[80:83], v[0:15]
	s_setprio 0
	ds_read_b64_tr_b16 v[64:65], v33 offset:40960
	ds_read_b64_tr_b16 v[66:67], v33 offset:43520
	ds_read_b64_tr_b16 v[78:79], v33 offset:43584
	ds_read_b64_tr_b16 v[76:77], v33 offset:41024
	v_cvt_pk_bf16_f32 v80, v84, v84
	v_cvt_pk_bf16_f32 v81, v84, v84
	v_cvt_pk_bf16_f32 v82, v84, v84
	v_cvt_pk_bf16_f32 v83, v84, v84
	s_setprio 1
	s_waitcnt lgkmcnt(6)
	v_mfma_f32_32x32x16_bf16 v[16:31], v[68:71], v[80:83], v[16:31]
	s_waitcnt lgkmcnt(4)
	v_mfma_f32_32x32x16_bf16 v[0:15], v[72:75], v[80:83], v[0:15]
	s_setprio 0
	v_cvt_pk_bf16_f32 v68, v84, v84
	v_cvt_pk_bf16_f32 v69, v84, v84
	v_cvt_pk_bf16_f32 v70, v84, v84
	v_cvt_pk_bf16_f32 v71, v84, v84
	s_setprio 1
	s_waitcnt lgkmcnt(2)
	v_mfma_f32_32x32x16_bf16 v[16:31], v[64:67], v[68:71], v[16:31]
	v_mov_b32_e32 v33, v87
	v_add_f32_e64 v152, v32, 0
	v_add_f32_e64 v153, v33, 0
	v_add_f32_e64 v32, -v152, neg(0)
	v_add_f32_e64 v33, -v153, neg(0)
	s_waitcnt lgkmcnt(0)
	v_mfma_f32_32x32x16_bf16 v[0:15], v[76:79], v[68:71], v[0:15]
	s_setprio 0
	v_add_u32_e32 v33, s59, v128
	s_waitcnt vmcnt(4)
	ds_write_b128 v61, v[34:37] offset:46080
	s_waitcnt vmcnt(3)
	ds_write_b128 v63, v[38:41] offset:46080
	s_waitcnt vmcnt(2)
	ds_write_b128 v90, v[46:49] offset:46080
	v_add_u32_e32 v34, v33, v170
	v_add_u32_e32 v33, v33, v171
	s_waitcnt vmcnt(1)
	ds_write_b128 v34, v[42:45]
	s_waitcnt vmcnt(0)
	ds_write_b128 v33, v[50:53]
	v_add_u32_e32 v33, s16, v62
	v_add_u32_e32 v176, 0x80, v33
	v_add_u32_e32 v33, s16, v60
	v_add_u32_e32 v177, 0x80, v33
	v_add_u32_e32 v33, s16, v89
	v_add_u32_e32 v182, 0x80, v33
	v_add_u32_e32 v33, s16, v88
	v_add_u32_e32 v183, 0x80, v33
	v_add_u32_e32 v33, s16, v85
	v_lshl_add_u64 v[156:157], s[0:1], 0, v[54:55]
	v_lshl_add_u64 v[158:159], s[0:1], 0, v[56:57]
	v_lshl_add_u64 v[160:161], s[0:1], 0, v[58:59]
	v_add_u32_e32 v184, 0x80, v33
	v_mov_b32_e32 v33, v32
	v_mov_b32_e32 v34, v32
	v_mov_b32_e32 v35, v32
	v_mov_b32_e32 v36, v32
	v_mov_b32_e32 v37, v32
	v_mov_b32_e32 v38, v32
	v_mov_b32_e32 v39, v32
	v_mov_b32_e32 v40, v32
	v_mov_b32_e32 v41, v32
	v_mov_b32_e32 v42, v32
	v_mov_b32_e32 v43, v32
	v_mov_b32_e32 v44, v32
	v_mov_b32_e32 v45, v32
	v_mov_b32_e32 v46, v32
	v_mov_b32_e32 v47, v32
	s_waitcnt lgkmcnt(0)
	s_barrier
	s_branch .LBB0_697
; #define LAS __attribute__((address_space(3)))
; template <bool DIFF> ...
;     ...
;     for (int t = 0; t < NT; ++t) {
;         const int buf = t & 1;
;         if (t + 1 < NT) ATT_GLOAD(t + 1);
;         if (t < nt_w) {
;             const LAS unsigned char* kb_ = lds + buf * BUFB; const LAS unsigned char* vb_ = kb_ + KTILEB;
;             f32x16 pr[2];
;             const LAS unsigned char* vbase = vb_ + (4 * hi + ((lane & 15) >> 2)) * VROWB + (sdv + ((lane >> 4) & 1) * 16 + (lane & 3) * 4) * 2;
;     ...
;             bf16x8 vfa[NDB], vfb[NDB];
;             {
;                 bf16x8 kf[2][NS];
; #pragma unroll
;                 for (int kb = 0; kb < 2; ++kb)
; #pragma unroll
;                     for (int st = 0; st < NS; ++st) kf[kb][st] = *(const LAS bf16x8*)(kb_ + (kb * 32 + l32) * KROWB + (s * DQK + st * 16 + hi * 8) * 2);
;                 VLOAD(vfa, 0);
;                 __builtin_amdgcn_sched_barrier(0);
;                 __builtin_amdgcn_s_setprio(1);
; #pragma unroll
;                 for (int st = 0; st < NS; ++st) {
;                     pr[0] = __builtin_amdgcn_mfma_f32_32x32x16_bf16(kf[0][st], qf[st], st == 0 ? negm : pr[0], 0, 0, 0);
;                     pr[1] = __builtin_amdgcn_mfma_f32_32x32x16_bf16(kf[1][st], qf[st], st == 0 ? negm : pr[1], 0, 0, 0); }
;                 __builtin_amdgcn_s_setprio(0);
;             }
;             const int tp0 = (t == 0) ? -16 : (t - 1) * 64;
;             if (DIFF) {
;                 if (tp0 + 63 - qpos_w > -128) {
; #pragma unroll
;                     for (int kb = 0; kb < 2; ++kb)
; #pragma unroll
;                         for (int r = 0; r < 16; ++r) { const int kvi = kb * 32 + 8 * (r >> 2) + 4 * hi + (r & 3); int idx = tp0 + kvi - qpos + 128; idx = idx < 0 ? 0 : idx; pr[kb][r] += lut[idx]; }
;                 }
;             }
;             const int nval = (t == 0) ? 16 : (t == NT - 1 ? lastv : 64);
;             if (nval < 64) {
; #pragma unroll
;                 for (int kb = 0; kb < 2; ++kb)
; #pragma unroll
;                     for (int r = 0; r < 16; ++r) { const int kvi = kb * 32 + 8 * (r >> 2) + 4 * hi + (r & 3); if (kvi >= nval) pr[kb][r] = -INFINITY; }
;             }
;             float mx;
;             { float a0 = fmaxf(fmaxf(pr[0][0], pr[0][1]), pr[0][2]), a1 = fmaxf(fmaxf(pr[1][0], pr[1][1]), pr[1][2]);
; #pragma unroll
.LBB0_695:
	v_add_u32_e32 v48, s39, v184
	v_add_u32_e32 v50, s39, v183
	v_mad_i64_i32 v[48:49], s[40:41], v48, s2, v[156:157]
	v_mad_i64_i32 v[50:51], s[40:41], v50, s2, v[158:159]
	global_load_dwordx4 v[124:127], v[48:49], off
	global_load_dwordx4 v[120:123], v[50:51], off
	v_add_u32_e32 v50, s39, v177
	v_add_u32_e32 v48, s39, v182
	v_ashrrev_i32_e32 v51, 31, v50
	v_mad_i64_i32 v[48:49], s[40:41], v48, s2, v[160:161]
	v_lshlrev_b64 v[50:51], 10, v[50:51]
	v_lshl_add_u64 v[50:51], v[154:155], 0, v[50:51]
	global_load_dwordx4 v[134:137], v[48:49], off
	global_load_dwordx4 v[130:133], v[50:51], off
	v_add_u32_e32 v48, s39, v176
	v_ashrrev_i32_e32 v49, 31, v48
	v_lshlrev_b64 v[48:49], 10, v[48:49]
	v_lshl_add_u64 v[48:49], v[154:155], 0, v[48:49]
	global_load_dwordx4 v[138:141], v[48:49], off
	s_and_b32 s40, s38, 1
.LBB0_696:
	s_xor_b32 s40, s40, 1
	s_mul_i32 s40, s40, 0xb400
	s_add_i32 s40, s40, 0
	v_add3_u32 v64, s40, v164, v165
	s_waitcnt vmcnt(4)
	ds_write_b128 v64, v[124:127]
	v_add3_u32 v64, s40, v166, v167
	s_waitcnt vmcnt(3)
	ds_write_b128 v64, v[120:123]
	v_add3_u32 v64, s40, v168, v169
	s_waitcnt vmcnt(2)
	ds_write_b128 v64, v[134:137]
	v_add_u32_e32 v64, s40, v128
	v_add_u32_e32 v65, v64, v170
	v_add_u32_e32 v64, v64, v171
	s_waitcnt vmcnt(1)
	ds_write_b128 v65, v[130:133] offset:25600
	s_waitcnt vmcnt(0)
	ds_write_b128 v64, v[138:141] offset:25600
.Ltail2_m1:
	s_add_i32 s39, s39, 64
	s_add_i32 s38, s38, 1
	s_cmp_lg_u32 s25, s39
	s_waitcnt lgkmcnt(0)
	s_barrier
	s_cbranch_scc0 .LBB0_702
.LBB0_697:
	s_and_b32 s40, s38, 1
	s_cmp_ge_u32 s38, s35
	s_cbranch_scc1 .LBB0_695
	s_mul_i32 s41, s40, 0xb400
	s_add_i32 s41, s41, 0
	v_add3_u32 v65, s41, v175, v174
	ds_read_b128 v[48:51], v65
	ds_read_b128 v[52:55], v65 offset:32
	ds_read_b128 v[56:59], v65 offset:64
	ds_read_b128 v[60:63], v65 offset:96
	ds_read_b128 v[186:189], v65 offset:128
	ds_read_b128 v[190:193], v65 offset:160
	ds_read_b128 v[202:205], v65 offset:12800
	ds_read_b128 v[206:209], v65 offset:12832
	ds_read_b128 v[210:213], v65 offset:12864
	ds_read_b128 v[214:217], v65 offset:12896
	ds_read_b128 v[218:221], v65 offset:12928
	ds_read_b128 v[222:225], v65 offset:12960
	v_add_u32_e32 v64, s41, v173
	v_add_u32_e32 v185, v64, v172
	ds_read_b64_tr_b16 v[142:143], v185 offset:25600
	ds_read_b64_tr_b16 v[144:145], v185 offset:28160
	ds_read_b64_tr_b16 v[148:149], v185 offset:28224
	ds_read_b64_tr_b16 v[146:147], v185 offset:25664
	s_setprio 1
	s_waitcnt lgkmcnt(14)
	v_mfma_f32_32x32x16_bf16 v[80:95], v[48:51], v[116:119], v[32:47]
	s_waitcnt lgkmcnt(9)
	v_mfma_f32_32x32x16_bf16 v[64:79], v[202:205], v[116:119], v[32:47]
	v_add_u32_e32 v48, s39, v184
	v_add_u32_e32 v50, s39, v183
	v_mad_i64_i32 v[48:49], s[40:41], v48, s2, v[156:157]
	v_mad_i64_i32 v[50:51], s[40:41], v50, s2, v[158:159]
	v_mfma_f32_32x32x16_bf16 v[80:95], v[52:55], v[112:115], v[80:95]
	global_load_dwordx4 v[124:127], v[48:49], off
	global_load_dwordx4 v[120:123], v[50:51], off
	s_waitcnt lgkmcnt(8)
	v_mfma_f32_32x32x16_bf16 v[64:79], v[206:209], v[112:115], v[64:79]
	v_add_u32_e32 v50, s39, v177
	v_add_u32_e32 v48, s39, v182
	v_ashrrev_i32_e32 v51, 31, v50
	v_mfma_f32_32x32x16_bf16 v[80:95], v[56:59], v[108:111], v[80:95]
	v_mad_i64_i32 v[48:49], s[40:41], v48, s2, v[160:161]
	v_lshlrev_b64 v[50:51], 10, v[50:51]
	v_lshl_add_u64 v[50:51], v[154:155], 0, v[50:51]
	s_waitcnt lgkmcnt(7)
	v_mfma_f32_32x32x16_bf16 v[64:79], v[210:213], v[108:111], v[64:79]
	global_load_dwordx4 v[134:137], v[48:49], off
	global_load_dwordx4 v[130:133], v[50:51], off
	v_mfma_f32_32x32x16_bf16 v[80:95], v[60:63], v[104:107], v[80:95]
	v_add_u32_e32 v48, s39, v176
	v_ashrrev_i32_e32 v49, 31, v48
	v_lshlrev_b64 v[48:49], 10, v[48:49]
	v_lshl_add_u64 v[48:49], v[154:155], 0, v[48:49]
	s_waitcnt lgkmcnt(6)
	v_mfma_f32_32x32x16_bf16 v[64:79], v[214:217], v[104:107], v[64:79]
	global_load_dwordx4 v[138:141], v[48:49], off
	s_and_b32 s40, s38, 1
	v_mfma_f32_32x32x16_bf16 v[80:95], v[186:189], v[100:103], v[80:95]
	s_waitcnt lgkmcnt(5)
	v_mfma_f32_32x32x16_bf16 v[64:79], v[218:221], v[100:103], v[64:79]
	v_mfma_f32_32x32x16_bf16 v[80:95], v[190:193], v[96:99], v[80:95]
	s_waitcnt lgkmcnt(4)
	v_mfma_f32_32x32x16_bf16 v[64:79], v[222:225], v[96:99], v[64:79]
	s_setprio 0
	s_nop 8
	v_max3_f32 v48, v80, v81, v82
	s_nop 0
	v_max3_f32 v49, v64, v65, v66
	v_max3_f32 v48, v48, v83, v84
	v_max3_f32 v49, v49, v67, v68
	v_max3_f32 v48, v48, v85, v86
	v_max3_f32 v49, v49, v69, v70
	v_max3_f32 v48, v48, v87, v88
	v_max3_f32 v49, v49, v71, v72
	v_max3_f32 v48, v48, v89, v90
	v_max3_f32 v49, v49, v73, v74
	v_max3_f32 v48, v48, v91, v92
	v_max3_f32 v49, v49, v75, v76
	v_max_f32_e32 v50, v79, v79
	v_max_f32_e32 v51, v95, v95
	v_max3_f32 v48, v48, v93, v94
	v_max3_f32 v49, v49, v77, v78
	v_max_f32_e32 v50, v51, v50
	v_max3_f32 v48, v48, v49, v50
	v_cmp_lt_f32_e32 vcc, s33, v48
	s_cbranch_vccz .LBB0_700
; template <bool DIFF> ...
;     ...
;             if (t == 0 || __any(mx > 8.0f)) {
;                 const float dl = (t == 0) ? mx : fmaxf(mx, 0.f);
;                 mrun += dl;
; #pragma unroll
;                 for (int r = 0; r < 16; ++r) negm[r] = -mrun;
;                 const float alpha = (t == 0) ? 1.f : __builtin_amdgcn_exp2f(-dl); lsum *= alpha;
; #pragma unroll
;                 for (int kb = 0; kb < 2; ++kb) pr[kb] = pr[kb] - dl;
; #pragma unroll
;                 for (int db = 0; db < NDB; ++db) o[db] = o[db] * alpha;
;             }
;             f32x2 ps2 = (f32x2){0.f, 0.f};
; #pragma unroll
;             for (int kb = 0; kb < 2; ++kb)
; #pragma unroll
;                 for (int r = 0; r < 16; r += 2) { const float e0 = __builtin_amdgcn_exp2f(pr[kb][r]), e1 = __builtin_amdgcn_exp2f(pr[kb][r + 1]); pr[kb][r] = e0; pr[kb][r + 1] = e1; ps2 += (f32x2){e0, e1}; }
;             lsum += ps2[0] + ps2[1];
;             __builtin_amdgcn_sched_barrier(0);
;             VLOAD(vfb, 1); __builtin_amdgcn_sched_barrier(0); PVMMA(vfa, 0); __builtin_amdgcn_sched_barrier(0);
;             VLOAD(vfa, 2); __builtin_amdgcn_sched_barrier(0); PVMMA(vfb, 1); __builtin_amdgcn_sched_barrier(0);
;             VLOAD(vfb, 3); __builtin_amdgcn_sched_barrier(0); PVMMA(vfa, 2); __builtin_amdgcn_sched_barrier(0);
;             PVMMA(vfb, 3);
;     ...
;         }
;         if (t + 1 < NT) ATT_LSTORE(buf ^ 1);
;         __syncthreads();
	ds_bpermute_b32 v49, v163, v48
	s_waitcnt lgkmcnt(0)
	v_max_f32_e32 v49, v49, v49
	v_max_f32_e32 v48, v48, v49
	v_max_f32_e32 v32, v48, v48
	v_max_f32_e32 v33, 0, v32
	v_exp_f32_e64 v34, -v33
	v_add_f32_e32 v152, v152, v33
	v_xor_b32_e32 v32, 0x80000000, v152
	v_sub_f32_e32 v80, v80, v33
	v_sub_f32_e32 v81, v81, v33
	v_sub_f32_e32 v82, v82, v33
	v_sub_f32_e32 v95, v95, v33
	v_sub_f32_e32 v83, v83, v33
	v_sub_f32_e32 v84, v84, v33
	v_sub_f32_e32 v85, v85, v33
	v_sub_f32_e32 v86, v86, v33
	v_sub_f32_e32 v87, v87, v33
	v_sub_f32_e32 v88, v88, v33
	v_sub_f32_e32 v89, v89, v33
	v_sub_f32_e32 v90, v90, v33
	v_sub_f32_e32 v91, v91, v33
	v_sub_f32_e32 v92, v92, v33
	v_sub_f32_e32 v93, v93, v33
	v_sub_f32_e32 v94, v94, v33
	v_sub_f32_e32 v64, v64, v33
	v_sub_f32_e32 v65, v65, v33
	v_sub_f32_e32 v66, v66, v33
	v_sub_f32_e32 v67, v67, v33
	v_sub_f32_e32 v68, v68, v33
	v_sub_f32_e32 v69, v69, v33
	v_sub_f32_e32 v70, v70, v33
	v_sub_f32_e32 v71, v71, v33
	v_sub_f32_e32 v72, v72, v33
	v_sub_f32_e32 v73, v73, v33
	v_sub_f32_e32 v74, v74, v33
	v_sub_f32_e32 v75, v75, v33
	v_sub_f32_e32 v76, v76, v33
	v_sub_f32_e32 v77, v77, v33
	v_sub_f32_e32 v78, v78, v33
	v_sub_f32_e32 v79, v79, v33
	v_pk_mul_f32 v[30:31], v[30:31], v[34:35] op_sel_hi:[1,0]
	v_pk_mul_f32 v[28:29], v[28:29], v[34:35] op_sel_hi:[1,0]
	v_pk_mul_f32 v[26:27], v[26:27], v[34:35] op_sel_hi:[1,0]
	v_pk_mul_f32 v[24:25], v[24:25], v[34:35] op_sel_hi:[1,0]
	v_pk_mul_f32 v[22:23], v[22:23], v[34:35] op_sel_hi:[1,0]
	v_pk_mul_f32 v[20:21], v[20:21], v[34:35] op_sel_hi:[1,0]
	v_pk_mul_f32 v[18:19], v[18:19], v[34:35] op_sel_hi:[1,0]
	v_pk_mul_f32 v[16:17], v[16:17], v[34:35] op_sel_hi:[1,0]
	v_pk_mul_f32 v[14:15], v[14:15], v[34:35] op_sel_hi:[1,0]
	v_pk_mul_f32 v[12:13], v[12:13], v[34:35] op_sel_hi:[1,0]
	v_pk_mul_f32 v[10:11], v[10:11], v[34:35] op_sel_hi:[1,0]
	v_pk_mul_f32 v[8:9], v[8:9], v[34:35] op_sel_hi:[1,0]
	v_pk_mul_f32 v[6:7], v[6:7], v[34:35] op_sel_hi:[1,0]
	v_pk_mul_f32 v[4:5], v[4:5], v[34:35] op_sel_hi:[1,0]
	v_pk_mul_f32 v[2:3], v[2:3], v[34:35] op_sel_hi:[1,0]
	v_pk_mul_f32 v[0:1], v[0:1], v[34:35] op_sel_hi:[1,0]
	v_mul_f32_e32 v153, v153, v34
	v_mov_b32_e32 v33, v32
	v_mov_b32_e32 v34, v32
	v_mov_b32_e32 v35, v32
	v_mov_b32_e32 v36, v32
	v_mov_b32_e32 v37, v32
	v_mov_b32_e32 v38, v32
	v_mov_b32_e32 v39, v32
	v_mov_b32_e32 v40, v32
	v_mov_b32_e32 v41, v32
	v_mov_b32_e32 v42, v32
	v_mov_b32_e32 v43, v32
	v_mov_b32_e32 v44, v32
	v_mov_b32_e32 v45, v32
	v_mov_b32_e32 v46, v32
	v_mov_b32_e32 v47, v32
	s_branch .LBB0_701
.LBB0_700:
.LBB0_701:
	ds_read_b64_tr_b16 v[202:203], v185 offset:30720
	ds_read_b64_tr_b16 v[204:205], v185 offset:33280
	ds_read_b64_tr_b16 v[206:207], v185 offset:30784
	ds_read_b64_tr_b16 v[208:209], v185 offset:33344
	v_exp_f32_e32 v210, v80
	v_exp_f32_e32 v211, v81
	v_exp_f32_e32 v212, v82
	v_exp_f32_e32 v213, v83
	v_pk_add_f32 v[54:55], v[210:211], 0 op_sel_hi:[1,0]
	v_exp_f32_e32 v214, v84
	v_exp_f32_e32 v215, v85
	v_pk_add_f32 v[54:55], v[212:213], v[54:55]
	v_exp_f32_e32 v80, v86
	v_exp_f32_e32 v81, v87
	v_pk_add_f32 v[54:55], v[214:215], v[54:55]
	v_cvt_pk_bf16_f32 v216, v210, v211
	v_cvt_pk_bf16_f32 v217, v212, v213
	v_cvt_pk_bf16_f32 v218, v214, v215
	v_cvt_pk_bf16_f32 v219, v80, v81
	s_setprio 1
	v_pk_add_f32 v[54:55], v[80:81], v[54:55]
	s_waitcnt lgkmcnt(4)
	v_mfma_f32_32x32x16_bf16 v[16:31], v[142:145], v[216:219], v[16:31]
	v_exp_f32_e32 v82, v88
	v_exp_f32_e32 v83, v89
	v_exp_f32_e32 v84, v90
	v_exp_f32_e32 v85, v91
	v_pk_add_f32 v[54:55], v[82:83], v[54:55]
	v_mfma_f32_32x32x16_bf16 v[0:15], v[146:149], v[216:219], v[0:15]
	v_exp_f32_e32 v86, v92
	v_exp_f32_e32 v87, v93
	v_exp_f32_e32 v88, v94
	v_exp_f32_e32 v89, v95
	v_pk_add_f32 v[54:55], v[84:85], v[54:55]
	v_pk_add_f32 v[54:55], v[86:87], v[54:55]
	ds_read_b64_tr_b16 v[220:221], v185 offset:35840
	ds_read_b64_tr_b16 v[222:223], v185 offset:38400
	ds_read_b64_tr_b16 v[226:227], v185 offset:38464
	ds_read_b64_tr_b16 v[224:225], v185 offset:35904
	v_cvt_pk_bf16_f32 v228, v82, v83
	v_cvt_pk_bf16_f32 v229, v84, v85
	v_cvt_pk_bf16_f32 v230, v86, v87
	v_cvt_pk_bf16_f32 v231, v88, v89
	v_pk_add_f32 v[54:55], v[88:89], v[54:55]
	s_waitcnt lgkmcnt(6)
	v_mfma_f32_32x32x16_bf16 v[16:31], v[202:205], v[228:231], v[16:31]
	v_exp_f32_e32 v90, v64
	v_exp_f32_e32 v91, v65
	v_exp_f32_e32 v92, v66
	v_exp_f32_e32 v93, v67
	v_pk_add_f32 v[54:55], v[90:91], v[54:55]
	s_waitcnt lgkmcnt(4)
	v_mfma_f32_32x32x16_bf16 v[0:15], v[206:209], v[228:231], v[0:15]
	v_exp_f32_e32 v94, v68
	v_exp_f32_e32 v95, v69
	v_exp_f32_e32 v198, v70
	v_exp_f32_e32 v199, v71
	v_pk_add_f32 v[54:55], v[92:93], v[54:55]
	v_pk_add_f32 v[54:55], v[94:95], v[54:55]
	ds_read_b64_tr_b16 v[202:203], v185 offset:40960
	ds_read_b64_tr_b16 v[204:205], v185 offset:43520
	ds_read_b64_tr_b16 v[208:209], v185 offset:43584
	ds_read_b64_tr_b16 v[206:207], v185 offset:41024
	v_cvt_pk_bf16_f32 v228, v90, v91
	v_cvt_pk_bf16_f32 v229, v92, v93
	v_cvt_pk_bf16_f32 v230, v94, v95
	v_cvt_pk_bf16_f32 v231, v198, v199
	v_pk_add_f32 v[54:55], v[198:199], v[54:55]
	s_waitcnt lgkmcnt(6)
	v_mfma_f32_32x32x16_bf16 v[16:31], v[220:223], v[228:231], v[16:31]
	v_exp_f32_e32 v72, v72
	v_exp_f32_e32 v73, v73
	v_exp_f32_e32 v74, v74
	v_exp_f32_e32 v75, v75
	v_pk_add_f32 v[54:55], v[72:73], v[54:55]
	s_waitcnt lgkmcnt(4)
	v_mfma_f32_32x32x16_bf16 v[0:15], v[224:227], v[228:231], v[0:15]
	v_exp_f32_e32 v76, v76
	v_exp_f32_e32 v77, v77
	v_exp_f32_e32 v78, v78
	v_exp_f32_e32 v79, v79
	v_pk_add_f32 v[54:55], v[74:75], v[54:55]
	v_pk_add_f32 v[54:55], v[76:77], v[54:55]
	v_cvt_pk_bf16_f32 v216, v72, v73
	v_cvt_pk_bf16_f32 v217, v74, v75
	v_cvt_pk_bf16_f32 v218, v76, v77
	v_cvt_pk_bf16_f32 v219, v78, v79
	v_pk_add_f32 v[54:55], v[78:79], v[54:55]
	s_nop 0
	v_add_f32_e32 v52, v54, v55
	s_waitcnt lgkmcnt(2)
	v_mfma_f32_32x32x16_bf16 v[16:31], v[202:205], v[216:219], v[16:31]
	v_add_f32_e32 v153, v153, v52
	s_xor_b32 s41, s40, 1
	s_mul_i32 s41, s41, 0xb400
	v_add3_u32 v64, s41, v164, v165
	s_waitcnt vmcnt(4)
	ds_write_b128 v64, v[124:127]
	v_add3_u32 v64, s41, v166, v167
	s_waitcnt vmcnt(3)
	ds_write_b128 v64, v[120:123]
	s_waitcnt lgkmcnt(2)
	v_mfma_f32_32x32x16_bf16 v[0:15], v[206:209], v[216:219], v[0:15]
	v_add3_u32 v64, s41, v168, v169
	s_waitcnt vmcnt(2)
	ds_write_b128 v64, v[134:137]
	v_add_u32_e32 v64, s41, v128
	v_add_u32_e32 v65, v64, v170
	v_add_u32_e32 v64, v64, v171
	s_waitcnt vmcnt(1)
	ds_write_b128 v65, v[130:133] offset:25600
	s_waitcnt vmcnt(0)
	ds_write_b128 v64, v[138:141] offset:25600
	s_setprio 0
	s_branch .Ltail2_m1

; #define LAS __attribute__((address_space(3)))
; __device__ __forceinline__ int tid_fresh() { int t = threadIdx.x; asm volatile("" : "+v"(t)); return t; }
; __device__ __forceinline__ u32x2 pk4(f32x4 v) { u32x2 w; w.x = pk2(v[0], v[1]); w.y = pk2(v[2], v[3]); return w; }
; template <bool DIFF> ...
;     ...
;     const int tid = tid_fresh(), lane = tid & 63, wid = __builtin_amdgcn_readfirstlane(tid >> 6), s = wid >> 2, l32 = lane & 31, hi = lane >> 5;
;     const int kcol0 = hx * (2 * DQK), vcol0 = hx * 128, sdv = DIFF ? 0 : s * 64;
;     LAS float* lut = (LAS float*)(lds + LUT_OFF);
;     u32x4 kst[NKC], vst[2];
;     ...
;     ATT_GLOAD(0);
;     if (DIFF) { if (tid < 192) lut[tid] = lutg[hx * 192 + tid] - lutg[hx * 192]; }
;     bf16x8 qf[NS];
;     { const int qi = l32 < nqv ? l32 : (nqv > 0 ? nqv - 1 : 0);
;       const bf16_t* qp = Qg + (size_t)(qrow_w + qi) * KP + (DIFF ? hx * 128 + s * 64 : (hx * 2 + s) * 96) + hi * 8;
; #pragma unroll
;       for (int st = 0; st < NS; ++st) qf[st] = *(const bf16x8*)(qp + st * 16); }
;     f32x16 o[NDB];
; #pragma unroll
;     for (int db = 0; db < NDB; ++db)
; #pragma unroll
;         for (int r = 0; r < 16; ++r) o[db][r] = 0.f;
;     float mrun = 0.f, lsum = 0.f; f32x16 negm;
; #pragma unroll
;     for (int r = 0; r < 16; ++r) negm[r] = 0.f;
;     ATT_LSTORE(0);
;     __syncthreads();
;     ...
;         if (l32 < nqv) {
;             bf16_t* op = Og + (size_t)(qrow_w + l32) * 512 + (hx * 2 + s) * 64 + 4 * hi;
; #pragma unroll
;             for (int db = 0; db < NDB; ++db)
; #pragma unroll
;                 for (int g4 = 0; g4 < 4; ++g4) { f32x4 v; v[0] = o[db][4 * g4] * inv; v[1] = o[db][4 * g4 + 1] * inv; v[2] = o[db][4 * g4 + 2] * inv; v[3] = o[db][4 * g4 + 3] * inv;
;                     *(u32x2*)(op + db * 32 + 8 * g4) = pk4(v); }
;         }
.LBB0_706:
	ds_bpermute_b32 v32, v163, v153
	s_add_u32 s26, s26, 0x45a10000
	s_addc_u32 s27, s27, 0
	s_lshl_b32 s24, s24, 6
	s_ashr_i32 s25, s24, 31
	s_waitcnt lgkmcnt(0)
	v_add_f32_e32 v32, v153, v32
	v_div_scale_f32 v33, s[38:39], v32, v32, 1.0
	v_rcp_f32_e32 v34, v33
	v_lshlrev_b32_e32 v128, 1, v162
	s_barrier
	v_fma_f32 v35, -v33, v34, 1.0
	v_fmac_f32_e32 v34, v35, v34
	v_div_scale_f32 v35, vcc, 1.0, v32, 1.0
	v_mul_f32_e32 v36, v35, v34
	v_fma_f32 v37, -v33, v36, v35
	v_fmac_f32_e32 v36, v37, v34
	v_fma_f32 v33, -v33, v36, v35
	v_div_fmas_f32 v33, v33, v34, v36
	v_div_fixup_f32 v34, v33, v32, 1.0
	v_lshlrev_b64 v[32:33], 10, v[150:151]
	v_lshl_add_u64 v[32:33], s[26:27], 0, v[32:33]
	v_lshl_add_u64 v[32:33], s[24:25], 1, v[32:33]
	v_mul_f32_e32 v16, v16, v34
	v_mul_f32_e32 v17, v17, v34
	v_lshl_add_u64 v[32:33], v[32:33], 0, v[128:129]
	v_mul_f32_e32 v18, v18, v34
	v_mul_f32_e32 v19, v19, v34
	v_cvt_pk_bf16_f32 v16, v16, v17
	v_cvt_pk_bf16_f32 v17, v18, v19
	global_store_dwordx2 v[32:33], v[16:17], off
	v_mul_f32_e32 v16, v20, v34
	v_mul_f32_e32 v17, v21, v34
	v_mul_f32_e32 v18, v22, v34
	v_mul_f32_e32 v19, v23, v34
	v_cvt_pk_bf16_f32 v16, v16, v17
	v_cvt_pk_bf16_f32 v17, v18, v19
	global_store_dwordx2 v[32:33], v[16:17], off offset:16
	v_mul_f32_e32 v16, v24, v34
	v_mul_f32_e32 v17, v25, v34
	v_mul_f32_e32 v18, v26, v34
	v_mul_f32_e32 v19, v27, v34
	v_cvt_pk_bf16_f32 v16, v16, v17
	v_cvt_pk_bf16_f32 v17, v18, v19
	global_store_dwordx2 v[32:33], v[16:17], off offset:32
	v_mul_f32_e32 v16, v28, v34
	v_mul_f32_e32 v17, v29, v34
	v_mul_f32_e32 v0, v0, v34
	v_mul_f32_e32 v18, v30, v34
	v_mul_f32_e32 v19, v31, v34
	v_cvt_pk_bf16_f32 v16, v16, v17
	v_cvt_pk_bf16_f32 v17, v18, v19
	global_store_dwordx2 v[32:33], v[16:17], off offset:48
	v_mul_f32_e32 v1, v1, v34
	v_cvt_pk_bf16_f32 v0, v0, v1
	v_mul_f32_e32 v2, v2, v34
	v_mul_f32_e32 v3, v3, v34
	v_cvt_pk_bf16_f32 v1, v2, v3
	global_store_dwordx2 v[32:33], v[0:1], off offset:64
	v_mul_f32_e32 v0, v4, v34
	v_mul_f32_e32 v1, v5, v34
	v_cvt_pk_bf16_f32 v0, v0, v1
	v_mul_f32_e32 v2, v6, v34
	v_mul_f32_e32 v3, v7, v34
	v_cvt_pk_bf16_f32 v1, v2, v3
	global_store_dwordx2 v[32:33], v[0:1], off offset:80
	v_mul_f32_e32 v0, v8, v34
	v_mul_f32_e32 v1, v9, v34
	v_cvt_pk_bf16_f32 v0, v0, v1
	v_mul_f32_e32 v2, v10, v34
	v_mul_f32_e32 v3, v11, v34
	v_cvt_pk_bf16_f32 v1, v2, v3
	global_store_dwordx2 v[32:33], v[0:1], off offset:96
	v_mul_f32_e32 v0, v12, v34
	v_mul_f32_e32 v1, v13, v34
	v_cvt_pk_bf16_f32 v0, v0, v1
	v_mov_b32_e32 v21, v194
	v_mov_b32_e32 v20, v194
	v_mul_f32_e32 v2, v14, v34
	v_mul_f32_e32 v3, v15, v34
	v_cvt_pk_bf16_f32 v1, v2, v3
	global_store_dwordx2 v[32:33], v[0:1], off offset:112
	v_mov_b64_e32 v[24:25], s[0:1]
	v_mul_hi_i32 v0, v20, s46
	v_add_u32_e32 v8, 0x400, v20
	v_lshrrev_b32_e32 v1, 31, v0
	v_ashrrev_i32_e32 v0, 2, v0
	v_mul_hi_i32 v9, v8, s46
	v_add_u32_e32 v85, v0, v1
	v_lshrrev_b32_e32 v10, 31, v9
	v_ashrrev_i32_e32 v9, 2, v9
	v_mad_u64_u32 v[22:23], s[24:25], v85, s47, v[20:21]
	v_add_u32_e32 v89, v9, v10
	v_lshlrev_b32_e32 v2, 3, v22
	v_mad_u64_u32 v[28:29], s[24:25], v89, s47, v[8:9]
	v_ashrrev_i32_e32 v3, 31, v2
	v_add_u32_e32 v16, 0x200, v20
	v_lshlrev_b32_e32 v10, 3, v28
	v_lshlrev_b64 v[54:55], 1, v[2:3]
	v_mul_hi_i32 v2, v16, s46
	v_ashrrev_i32_e32 v11, 31, v10
	v_lshrrev_b32_e32 v3, 31, v2
	v_ashrrev_i32_e32 v2, 2, v2
	v_lshlrev_b64 v[60:61], 1, v[10:11]
	v_lshlrev_b32_e32 v10, 4, v20
	v_ashrrev_i32_e32 v58, 4, v20
	v_add_u32_e32 v88, v2, v3
	v_and_b32_e32 v128, 0xf0, v10
	v_ashrrev_i32_e32 v59, 31, v58
	v_mad_u64_u32 v[26:27], s[24:25], v88, s47, v[16:17]
	v_lshl_add_u64 v[154:155], s[28:29], 0, v[128:129]
	v_lshlrev_b64 v[10:11], 10, v[58:59]
	v_ashrrev_i32_e32 v62, 4, v16
	v_lshlrev_b32_e32 v4, 3, v26
	v_lshl_add_u64 v[10:11], v[154:155], 0, v[10:11]
	v_ashrrev_i32_e32 v63, 31, v62
	v_add_u32_e32 v0, 0xa600, v85
	v_add_u32_e32 v2, 0xa600, v88
	v_ashrrev_i32_e32 v5, 31, v4
	v_add_co_u32_e32 v12, vcc, s48, v10
	v_lshlrev_b64 v[16:17], 10, v[62:63]
	v_mad_i64_i32 v[0:1], s[24:25], v0, s2, v[24:25]
	v_mad_i64_i32 v[2:3], s[24:25], v2, s2, v[24:25]
	v_lshlrev_b64 v[56:57], 1, v[4:5]
	v_add_u32_e32 v8, 0xa600, v89
	v_addc_co_u32_e32 v13, vcc, 0, v11, vcc
	v_lshl_add_u64 v[16:17], v[154:155], 0, v[16:17]
	v_lshl_add_u64 v[0:1], v[0:1], 0, v[54:55]
	v_lshl_add_u64 v[4:5], v[2:3], 0, v[56:57]
	v_mad_i64_i32 v[8:9], s[24:25], v8, s2, v[24:25]
	v_add_co_u32_e32 v16, vcc, s48, v16
	global_load_dwordx4 v[0:3], v[0:1], off
	s_nop 0
	global_load_dwordx4 v[4:7], v[4:5], off
	v_lshl_add_u64 v[8:9], v[8:9], 0, v[60:61]
	v_addc_co_u32_e32 v17, vcc, 0, v17, vcc
	global_load_dwordx4 v[8:11], v[8:9], off
	s_nop 0
	global_load_dwordx4 v[12:15], v[12:13], off
	v_readfirstlane_b32 s25, v21
	global_load_dwordx4 v[16:19], v[16:17], off
	s_xor_b32 s24, s17, 62
	s_bfe_u32 s28, s25, 0x10007
	s_or_b32 s17, s28, s24
	s_lshr_b32 s25, s25, 1
	s_lshl_b32 s17, s17, 6
	s_and_b32 s25, s25, 32
	s_or_b32 s17, s17, s25
	s_or_b32 s17, s17, s20
	v_readfirstlane_b32 s20, v20
	v_and_b32_e32 v21, 31, v20
	s_ashr_i32 s20, s20, 8
	v_or_b32_e32 v150, s17, v21
	v_mov_b64_e32 v[30:31], s[18:19]
	v_mad_i64_i32 v[30:31], s[18:19], v150, s2, v[30:31]
	s_add_i32 s17, s20, s23
	s_mul_i32 s18, s17, 0x60
	v_bfe_u32 v23, v20, 5, 1
	s_ashr_i32 s19, s18, 31
	v_lshl_add_u64 v[30:31], s[18:19], 1, v[30:31]
	v_lshlrev_b32_e32 v32, 4, v23
	v_mov_b32_e32 v33, v129
	v_mul_lo_u32 v164, v85, s58
	v_lshlrev_b32_e32 v165, 4, v22
	v_lshl_add_u64 v[30:31], v[30:31], 0, v[32:33]
	v_add3_u32 v59, 0, v164, v165
	global_load_dwordx4 v[116:119], v[30:31], off
	global_load_dwordx4 v[112:115], v[30:31], off offset:32
	global_load_dwordx4 v[108:111], v[30:31], off offset:64
	global_load_dwordx4 v[104:107], v[30:31], off offset:96
	global_load_dwordx4 v[100:103], v[30:31], off offset:128
	global_load_dwordx4 v[96:99], v[30:31], off offset:160
	v_mul_lo_u32 v166, v88, s58
	v_lshlrev_b32_e32 v167, 4, v26
	v_mul_lo_u32 v168, v89, s58
	v_lshlrev_b32_e32 v169, 4, v28
	v_mul_lo_u32 v170, v58, s75
	v_mul_lo_u32 v171, v62, s75
	v_add3_u32 v63, 0, v166, v167
	v_add3_u32 v90, 0, v168, v169
	v_lshlrev_b32_e32 v162, 2, v23
	v_mul_u32_u24_e32 v175, 0x190, v21
	v_ashrrev_i32_e32 v151, 31, v150
	s_waitcnt vmcnt(10)
	ds_write_b128 v59, v[0:3]
	v_add_u32_e32 v0, 0, v128
	v_add_u32_e32 v1, v0, v170
	v_add_u32_e32 v0, v0, v171
	s_waitcnt vmcnt(9)
	ds_write_b128 v63, v[4:7]
	s_waitcnt vmcnt(8)
	ds_write_b128 v90, v[8:11]
	s_waitcnt vmcnt(7)
	ds_write_b128 v1, v[12:15] offset:25600
	s_waitcnt vmcnt(6)
	ds_write_b128 v0, v[16:19] offset:25600
	v_add_u32_e32 v0, s22, v85
	v_add_u32_e32 v2, s22, v88
	v_mad_i64_i32 v[0:1], s[18:19], v0, s2, v[24:25]
	v_mad_i64_i32 v[2:3], s[18:19], v2, s2, v[24:25]
	v_lshl_add_u64 v[0:1], v[0:1], 0, v[54:55]
	v_lshl_add_u64 v[2:3], v[2:3], 0, v[56:57]
	s_waitcnt lgkmcnt(0)
	s_barrier
; #define LAS __attribute__((address_space(3)))
; template <bool DIFF> ...
;     ...
;     for (int t = 0; t < NT; ++t) {
;         const int buf = t & 1;
;         if (t + 1 < NT) ATT_GLOAD(t + 1);
;         if (t < nt_w) {
;             const LAS unsigned char* kb_ = lds + buf * BUFB; const LAS unsigned char* vb_ = kb_ + KTILEB;
;             f32x16 pr[2];
;             const LAS unsigned char* vbase = vb_ + (4 * hi + ((lane & 15) >> 2)) * VROWB + (sdv + ((lane >> 4) & 1) * 16 + (lane & 3) * 4) * 2;
;     ...
;             bf16x8 vfa[NDB], vfb[NDB];
;             {
;                 bf16x8 kf[2][NS];
; #pragma unroll
;                 for (int kb = 0; kb < 2; ++kb)
; #pragma unroll
;                     for (int st = 0; st < NS; ++st) kf[kb][st] = *(const LAS bf16x8*)(kb_ + (kb * 32 + l32) * KROWB + (s * DQK + st * 16 + hi * 8) * 2);
;                 VLOAD(vfa, 0);
;                 __builtin_amdgcn_sched_barrier(0);
;                 __builtin_amdgcn_s_setprio(1);
; #pragma unroll
;                 for (int st = 0; st < NS; ++st) {
;                     pr[0] = __builtin_amdgcn_mfma_f32_32x32x16_bf16(kf[0][st], qf[st], st == 0 ? negm : pr[0], 0, 0, 0);
;                     pr[1] = __builtin_amdgcn_mfma_f32_32x32x16_bf16(kf[1][st], qf[st], st == 0 ? negm : pr[1], 0, 0, 0); }
;                 __builtin_amdgcn_s_setprio(0);
;             }
;             const int tp0 = (t == 0) ? -16 : (t - 1) * 64;
;             if (DIFF) {
;                 if (tp0 + 63 - qpos_w > -128) {
; #pragma unroll
;                     for (int kb = 0; kb < 2; ++kb)
; #pragma unroll
;                         for (int r = 0; r < 16; ++r) { const int kvi = kb * 32 + 8 * (r >> 2) + 4 * hi + (r & 3); int idx = tp0 + kvi - qpos + 128; idx = idx < 0 ? 0 : idx; pr[kb][r] += lut[idx]; }
;                 }
;             }
;             const int nval = (t == 0) ? 16 : (t == NT - 1 ? lastv : 64);
;             if (nval < 64) {
; #pragma unroll
;                 for (int kb = 0; kb < 2; ++kb)
; #pragma unroll
;                     for (int r = 0; r < 16; ++r) { const int kvi = kb * 32 + 8 * (r >> 2) + 4 * hi + (r & 3); if (kvi >= nval) pr[kb][r] = -INFINITY; }
;             }
;             float mx;
;             { float a0 = fmaxf(fmaxf(pr[0][0], pr[0][1]), pr[0][2]), a1 = fmaxf(fmaxf(pr[1][0], pr[1][1]), pr[1][2]);
; #pragma unroll
	global_load_dwordx4 v[34:37], v[0:1], off
	global_load_dwordx4 v[38:41], v[2:3], off
	v_add_u32_e32 v0, s22, v89
	v_add_u32_e32 v2, s22, v58
	v_mad_i64_i32 v[0:1], s[18:19], v0, s2, v[24:25]
	v_ashrrev_i32_e32 v3, 31, v2
	v_lshl_add_u64 v[0:1], v[0:1], 0, v[60:61]
	v_lshlrev_b64 v[2:3], 10, v[2:3]
	v_lshl_add_u64 v[2:3], v[154:155], 0, v[2:3]
	global_load_dwordx4 v[46:49], v[0:1], off
	global_load_dwordx4 v[42:45], v[2:3], off
	v_add_u32_e32 v0, s22, v62
	v_ashrrev_i32_e32 v1, 31, v0
	v_lshlrev_b64 v[0:1], 10, v[0:1]
	v_lshl_add_u64 v[0:1], v[154:155], 0, v[0:1]
	global_load_dwordx4 v[50:53], v[0:1], off
	v_lshrrev_b32_e32 v0, 2, v20
	s_lshl_b32 s22, s20, 6
	v_and_or_b32 v0, v0, 3, v162
	v_lshlrev_b32_e32 v1, 2, v20
	s_mulk_i32 s20, 0xc0
	v_mul_u32_u24_e32 v173, 0x140, v0
	v_and_b32_e32 v0, 16, v20
	v_and_b32_e32 v1, 12, v1
	v_or_b32_e32 v174, s20, v32
	v_or3_b32 v0, s22, v0, v1
	v_add3_u32 v5, 0, v175, v174
	v_and_b32_e32 v4, 63, v20
	v_lshlrev_b32_e32 v172, 1, v0
	ds_read_b128 v[0:3], v5
	ds_read_b128 v[16:19], v5 offset:32
	ds_read_b128 v[20:23], v5 offset:64
	ds_read_b128 v[24:27], v5 offset:96
	ds_read_b128 v[28:31], v5 offset:128
	ds_read_b128 v[64:67], v5 offset:160
	v_add3_u32 v33, 0, v173, v172
	ds_read_b64_tr_b16 v[68:69], v33 offset:25600
	ds_read_b64_tr_b16 v[70:71], v33 offset:28160
	ds_read_b64_tr_b16 v[74:75], v33 offset:28224
	ds_read_b64_tr_b16 v[72:73], v33 offset:25664
	s_add_i32 s19, s24, s28
	v_lshlrev_b32_e32 v4, 2, v4
	s_mov_b32 s18, 1
	s_add_i32 s19, s19, 2
	s_mov_b32 s20, 0
	v_xor_b32_e32 v163, 0x80, v4
	s_setprio 1
	s_waitcnt vmcnt(10) lgkmcnt(9)
	v_mfma_f32_32x32x16_bf16 v[0:15], v[0:3], v[116:119], 0
	s_waitcnt vmcnt(9) lgkmcnt(8)
	v_mfma_f32_32x32x16_bf16 v[0:15], v[16:19], v[112:115], v[0:15]
	s_waitcnt vmcnt(8) lgkmcnt(7)
	v_mfma_f32_32x32x16_bf16 v[0:15], v[20:23], v[108:111], v[0:15]
	s_waitcnt vmcnt(7) lgkmcnt(6)
	v_mfma_f32_32x32x16_bf16 v[0:15], v[24:27], v[104:107], v[0:15]
	s_waitcnt vmcnt(6) lgkmcnt(5)
	v_mfma_f32_32x32x16_bf16 v[0:15], v[28:31], v[100:103], v[0:15]
	s_waitcnt vmcnt(5) lgkmcnt(4)
	v_mfma_f32_32x32x16_bf16 v[0:15], v[64:67], v[96:99], v[0:15]
	s_setprio 0
	s_nop 10
	v_max3_f32 v8, v0, v1, v2
	v_max3_f32 v8, v8, v3, v4
	v_max3_f32 v8, v8, v5, v6
	s_mov_b32 s22, 0xff800000
	v_max3_f32 v8, v8, v7, s22
	ds_bpermute_b32 v9, v163, v8
	s_waitcnt lgkmcnt(0)
	v_max_f32_e32 v9, v9, v9
	v_max_f32_e32 v32, v8, v9
	v_sub_f32_e32 v1, v1, v32
	v_sub_f32_e32 v0, v0, v32
	v_sub_f32_e32 v9, v7, v32
	v_sub_f32_e32 v8, v6, v32
	v_sub_f32_e32 v7, v5, v32
	v_sub_f32_e32 v6, v4, v32
	v_sub_f32_e32 v5, v3, v32
	v_sub_f32_e32 v4, v2, v32
	v_exp_f32_e32 v0, v0
	v_exp_f32_e32 v1, v1
	v_exp_f32_e32 v4, v4
	v_exp_f32_e32 v5, v5
	v_exp_f32_e32 v6, v6
	v_exp_f32_e32 v7, v7
	v_sub_f32_e32 v10, 0xff800000, v32
	v_exp_f32_e32 v8, v8
	v_exp_f32_e32 v9, v9
	v_pk_add_f32 v[2:3], v[0:1], 0 op_sel_hi:[1,0]
	v_exp_f32_e32 v84, v10
	v_pk_add_f32 v[2:3], v[4:5], v[2:3]
	s_nop 0
	v_pk_add_f32 v[2:3], v[6:7], v[2:3]
	s_nop 0
	v_pk_add_f32 v[2:3], v[8:9], v[2:3]
	s_nop 0
	v_pk_add_f32 v[2:3], v[84:85], v[2:3] op_sel_hi:[0,1]
	v_pk_add_f32 v[2:3], v[84:85], v[2:3] op_sel_hi:[0,1]
	v_pk_add_f32 v[2:3], v[84:85], v[2:3] op_sel_hi:[0,1]
	v_pk_add_f32 v[2:3], v[84:85], v[2:3] op_sel_hi:[0,1]
	v_pk_add_f32 v[2:3], v[84:85], v[2:3] op_sel_hi:[0,1]
	v_pk_add_f32 v[2:3], v[84:85], v[2:3] op_sel_hi:[0,1]
	v_pk_add_f32 v[2:3], v[84:85], v[2:3] op_sel_hi:[0,1]
	v_pk_add_f32 v[2:3], v[84:85], v[2:3] op_sel_hi:[0,1]
	v_pk_add_f32 v[2:3], v[84:85], v[2:3] op_sel_hi:[0,1]
	v_pk_add_f32 v[2:3], v[84:85], v[2:3] op_sel_hi:[0,1]
	v_pk_add_f32 v[2:3], v[84:85], v[2:3] op_sel_hi:[0,1]
	v_pk_add_f32 v[2:3], v[84:85], v[2:3] op_sel_hi:[0,1]
	v_pk_add_f32 v[86:87], v[2:3], v[2:3] op_sel_hi:[0,1]
	ds_read_b64_tr_b16 v[64:65], v33 offset:30720
	ds_read_b64_tr_b16 v[66:67], v33 offset:33280
	ds_read_b64_tr_b16 v[76:77], v33 offset:30784
	ds_read_b64_tr_b16 v[78:79], v33 offset:33344
	v_cvt_pk_bf16_f32 v0, v0, v1
	v_cvt_pk_bf16_f32 v1, v4, v5
	v_cvt_pk_bf16_f32 v2, v6, v7
	v_cvt_pk_bf16_f32 v3, v8, v9
	s_setprio 1
	v_mfma_f32_32x32x16_bf16 v[16:31], v[68:71], v[0:3], 0
	v_mfma_f32_32x32x16_bf16 v[0:15], v[72:75], v[0:3], 0
	s_setprio 0
	ds_read_b64_tr_b16 v[68:69], v33 offset:35840
	ds_read_b64_tr_b16 v[70:71], v33 offset:38400
	ds_read_b64_tr_b16 v[74:75], v33 offset:38464
	ds_read_b64_tr_b16 v[72:73], v33 offset:35904
	v_cvt_pk_bf16_f32 v80, v84, v84
	v_cvt_pk_bf16_f32 v81, v84, v84
	v_cvt_pk_bf16_f32 v82, v84, v84
	v_cvt_pk_bf16_f32 v83, v84, v84
	s_setprio 1
	s_waitcnt lgkmcnt(6)
	v_mfma_f32_32x32x16_bf16 v[16:31], v[64:67], v[80:83], v[16:31]
	s_waitcnt lgkmcnt(4)
	v_mfma_f32_32x32x16_bf16 v[0:15], v[76:79], v[80:83], v[0:15]
	s_setprio 0
	ds_read_b64_tr_b16 v[64:65], v33 offset:40960
	ds_read_b64_tr_b16 v[66:67], v33 offset:43520
	ds_read_b64_tr_b16 v[78:79], v33 offset:43584
	ds_read_b64_tr_b16 v[76:77], v33 offset:41024
	v_cvt_pk_bf16_f32 v80, v84, v84
	v_cvt_pk_bf16_f32 v81, v84, v84
	v_cvt_pk_bf16_f32 v82, v84, v84
	v_cvt_pk_bf16_f32 v83, v84, v84
	s_setprio 1
	s_waitcnt lgkmcnt(6)
	v_mfma_f32_32x32x16_bf16 v[16:31], v[68:71], v[80:83], v[16:31]
	s_waitcnt lgkmcnt(4)
	v_mfma_f32_32x32x16_bf16 v[0:15], v[72:75], v[80:83], v[0:15]
	s_setprio 0
	v_cvt_pk_bf16_f32 v68, v84, v84
	v_cvt_pk_bf16_f32 v69, v84, v84
	v_cvt_pk_bf16_f32 v70, v84, v84
	v_cvt_pk_bf16_f32 v71, v84, v84
	s_setprio 1
	s_waitcnt lgkmcnt(2)
	v_mfma_f32_32x32x16_bf16 v[16:31], v[64:67], v[68:71], v[16:31]
	v_mov_b32_e32 v33, v87
	v_add_f32_e64 v152, v32, 0
	v_add_f32_e64 v153, v33, 0
	v_add_f32_e64 v32, -v152, neg(0)
	v_add_f32_e64 v33, -v153, neg(0)
	s_waitcnt lgkmcnt(0)
	v_mfma_f32_32x32x16_bf16 v[0:15], v[76:79], v[68:71], v[0:15]
	s_setprio 0
	v_add_u32_e32 v33, s59, v128
	s_waitcnt vmcnt(4)
	ds_write_b128 v59, v[34:37] offset:46080
	s_waitcnt vmcnt(3)
	ds_write_b128 v63, v[38:41] offset:46080
	s_waitcnt vmcnt(2)
	ds_write_b128 v90, v[46:49] offset:46080
	v_add_u32_e32 v34, v33, v170
	v_add_u32_e32 v33, v33, v171
	s_waitcnt vmcnt(1)
	ds_write_b128 v34, v[42:45]
	s_waitcnt vmcnt(0)
	ds_write_b128 v33, v[50:53]
	v_add_u32_e32 v33, s16, v62
	v_add_u32_e32 v176, 0x80, v33
	v_add_u32_e32 v33, s16, v58
	v_add_u32_e32 v177, 0x80, v33
	v_add_u32_e32 v33, s16, v89
	v_add_u32_e32 v182, 0x80, v33
	v_add_u32_e32 v33, s16, v88
	v_lshl_add_u64 v[156:157], s[0:1], 0, v[54:55]
	v_lshl_add_u64 v[158:159], s[0:1], 0, v[56:57]
	v_lshl_add_u64 v[160:161], s[0:1], 0, v[60:61]
	s_lshl_b32 s0, s24, 6
	v_add_u32_e32 v183, 0x80, v33
	v_add_u32_e32 v33, s16, v85
	s_add_i32 s0, s0, 64
	v_add_u32_e32 v184, 0x80, v33
	v_mov_b32_e32 v33, v32
	v_mov_b32_e32 v34, v32
	v_mov_b32_e32 v35, v32
	v_mov_b32_e32 v36, v32
	v_mov_b32_e32 v37, v32
	v_mov_b32_e32 v38, v32
	v_mov_b32_e32 v39, v32
	v_mov_b32_e32 v40, v32
	v_mov_b32_e32 v41, v32
	v_mov_b32_e32 v42, v32
	v_mov_b32_e32 v43, v32
	v_mov_b32_e32 v44, v32
	v_mov_b32_e32 v45, v32
	v_mov_b32_e32 v46, v32
	v_mov_b32_e32 v47, v32
	s_waitcnt lgkmcnt(0)
	s_barrier
	s_branch .LBB0_709
; #define LAS __attribute__((address_space(3)))
; template <bool DIFF> ...
;     ...
;     for (int t = 0; t < NT; ++t) {
;         const int buf = t & 1;
;         if (t + 1 < NT) ATT_GLOAD(t + 1);
;         if (t < nt_w) {
;             const LAS unsigned char* kb_ = lds + buf * BUFB; const LAS unsigned char* vb_ = kb_ + KTILEB;
;             f32x16 pr[2];
;             const LAS unsigned char* vbase = vb_ + (4 * hi + ((lane & 15) >> 2)) * VROWB + (sdv + ((lane >> 4) & 1) * 16 + (lane & 3) * 4) * 2;
;     ...
;             bf16x8 vfa[NDB], vfb[NDB];
;             {
;                 bf16x8 kf[2][NS];
; #pragma unroll
;                 for (int kb = 0; kb < 2; ++kb)
; #pragma unroll
;                     for (int st = 0; st < NS; ++st) kf[kb][st] = *(const LAS bf16x8*)(kb_ + (kb * 32 + l32) * KROWB + (s * DQK + st * 16 + hi * 8) * 2);
;                 VLOAD(vfa, 0);
;                 __builtin_amdgcn_sched_barrier(0);
;                 __builtin_amdgcn_s_setprio(1);
; #pragma unroll
;                 for (int st = 0; st < NS; ++st) {
;                     pr[0] = __builtin_amdgcn_mfma_f32_32x32x16_bf16(kf[0][st], qf[st], st == 0 ? negm : pr[0], 0, 0, 0);
;                     pr[1] = __builtin_amdgcn_mfma_f32_32x32x16_bf16(kf[1][st], qf[st], st == 0 ? negm : pr[1], 0, 0, 0); }
;                 __builtin_amdgcn_s_setprio(0);
;             }
;             const int tp0 = (t == 0) ? -16 : (t - 1) * 64;
;             if (DIFF) {
;                 if (tp0 + 63 - qpos_w > -128) {
; #pragma unroll
;                     for (int kb = 0; kb < 2; ++kb)
; #pragma unroll
;                         for (int r = 0; r < 16; ++r) { const int kvi = kb * 32 + 8 * (r >> 2) + 4 * hi + (r & 3); int idx = tp0 + kvi - qpos + 128; idx = idx < 0 ? 0 : idx; pr[kb][r] += lut[idx]; }
;                 }
;             }
;             const int nval = (t == 0) ? 16 : (t == NT - 1 ? lastv : 64);
;             if (nval < 64) {
; #pragma unroll
;                 for (int kb = 0; kb < 2; ++kb)
; #pragma unroll
;                     for (int r = 0; r < 16; ++r) { const int kvi = kb * 32 + 8 * (r >> 2) + 4 * hi + (r & 3); if (kvi >= nval) pr[kb][r] = -INFINITY; }
;             }
;             float mx;
;             { float a0 = fmaxf(fmaxf(pr[0][0], pr[0][1]), pr[0][2]), a1 = fmaxf(fmaxf(pr[1][0], pr[1][1]), pr[1][2]);
; #pragma unroll
.LBB0_707:
	v_add_u32_e32 v48, s20, v184
	v_add_u32_e32 v50, s20, v183
	v_mad_i64_i32 v[48:49], s[22:23], v48, s2, v[156:157]
	v_mad_i64_i32 v[50:51], s[22:23], v50, s2, v[158:159]
	global_load_dwordx4 v[124:127], v[48:49], off
	global_load_dwordx4 v[120:123], v[50:51], off
	v_add_u32_e32 v50, s20, v177
	v_add_u32_e32 v48, s20, v182
	v_ashrrev_i32_e32 v51, 31, v50
	v_mad_i64_i32 v[48:49], s[22:23], v48, s2, v[160:161]
	v_lshlrev_b64 v[50:51], 10, v[50:51]
	v_lshl_add_u64 v[50:51], v[154:155], 0, v[50:51]
	global_load_dwordx4 v[134:137], v[48:49], off
	global_load_dwordx4 v[130:133], v[50:51], off
	v_add_u32_e32 v48, s20, v176
	v_ashrrev_i32_e32 v49, 31, v48
	v_lshlrev_b64 v[48:49], 10, v[48:49]
	v_lshl_add_u64 v[48:49], v[154:155], 0, v[48:49]
	global_load_dwordx4 v[138:141], v[48:49], off
.LBB0_708:
	s_xor_b32 s1, s1, 1
	s_mul_i32 s1, s1, 0xb400
	s_add_i32 s1, s1, 0
	v_add3_u32 v64, s1, v164, v165
	s_waitcnt vmcnt(4)
	ds_write_b128 v64, v[124:127]
	v_add3_u32 v64, s1, v166, v167
	s_waitcnt vmcnt(3)
	ds_write_b128 v64, v[120:123]
	v_add3_u32 v64, s1, v168, v169
	s_waitcnt vmcnt(2)
	ds_write_b128 v64, v[134:137]
	v_add_u32_e32 v64, s1, v128
	v_add_u32_e32 v65, v64, v170
	v_add_u32_e32 v64, v64, v171
	s_waitcnt vmcnt(1)
	ds_write_b128 v65, v[130:133] offset:25600
	s_waitcnt vmcnt(0)
	ds_write_b128 v64, v[138:141] offset:25600
.Ltail2_m2:
	s_add_i32 s20, s20, 64
	s_add_i32 s18, s18, 1
	s_cmp_lg_u32 s0, s20
	s_waitcnt lgkmcnt(0)
	s_barrier
	s_cbranch_scc0 .LBB0_714
.LBB0_709:
	s_and_b32 s1, s18, 1
	s_cmp_ge_u32 s18, s19
	s_cbranch_scc1 .LBB0_707
	s_mul_i32 s16, s1, 0xb400
	s_add_i32 s16, s16, 0
	v_add3_u32 v65, s16, v175, v174
	ds_read_b128 v[48:51], v65
	ds_read_b128 v[52:55], v65 offset:32
	ds_read_b128 v[56:59], v65 offset:64
	ds_read_b128 v[60:63], v65 offset:96
	ds_read_b128 v[186:189], v65 offset:128
	ds_read_b128 v[190:193], v65 offset:160
	ds_read_b128 v[202:205], v65 offset:12800
	ds_read_b128 v[206:209], v65 offset:12832
	ds_read_b128 v[210:213], v65 offset:12864
	ds_read_b128 v[214:217], v65 offset:12896
	ds_read_b128 v[218:221], v65 offset:12928
	ds_read_b128 v[222:225], v65 offset:12960
	v_add_u32_e32 v64, s16, v173
	v_add_u32_e32 v185, v64, v172
	ds_read_b64_tr_b16 v[142:143], v185 offset:25600
	ds_read_b64_tr_b16 v[144:145], v185 offset:28160
	ds_read_b64_tr_b16 v[148:149], v185 offset:28224
	ds_read_b64_tr_b16 v[146:147], v185 offset:25664
	s_setprio 1
	s_waitcnt lgkmcnt(14)
	v_mfma_f32_32x32x16_bf16 v[80:95], v[48:51], v[116:119], v[32:47]
	s_waitcnt lgkmcnt(9)
	v_mfma_f32_32x32x16_bf16 v[64:79], v[202:205], v[116:119], v[32:47]
	v_add_u32_e32 v48, s20, v184
	v_add_u32_e32 v50, s20, v183
	v_mad_i64_i32 v[48:49], s[22:23], v48, s2, v[156:157]
	v_mad_i64_i32 v[50:51], s[22:23], v50, s2, v[158:159]
	v_mfma_f32_32x32x16_bf16 v[80:95], v[52:55], v[112:115], v[80:95]
	global_load_dwordx4 v[124:127], v[48:49], off
	global_load_dwordx4 v[120:123], v[50:51], off
	s_waitcnt lgkmcnt(8)
	v_mfma_f32_32x32x16_bf16 v[64:79], v[206:209], v[112:115], v[64:79]
	v_add_u32_e32 v50, s20, v177
	v_add_u32_e32 v48, s20, v182
	v_ashrrev_i32_e32 v51, 31, v50
	v_mfma_f32_32x32x16_bf16 v[80:95], v[56:59], v[108:111], v[80:95]
	v_mad_i64_i32 v[48:49], s[22:23], v48, s2, v[160:161]
	v_lshlrev_b64 v[50:51], 10, v[50:51]
	v_lshl_add_u64 v[50:51], v[154:155], 0, v[50:51]
	s_waitcnt lgkmcnt(7)
	v_mfma_f32_32x32x16_bf16 v[64:79], v[210:213], v[108:111], v[64:79]
	global_load_dwordx4 v[134:137], v[48:49], off
	global_load_dwordx4 v[130:133], v[50:51], off
	v_mfma_f32_32x32x16_bf16 v[80:95], v[60:63], v[104:107], v[80:95]
	v_add_u32_e32 v48, s20, v176
	v_ashrrev_i32_e32 v49, 31, v48
	v_lshlrev_b64 v[48:49], 10, v[48:49]
	v_lshl_add_u64 v[48:49], v[154:155], 0, v[48:49]
	s_waitcnt lgkmcnt(6)
	v_mfma_f32_32x32x16_bf16 v[64:79], v[214:217], v[104:107], v[64:79]
	global_load_dwordx4 v[138:141], v[48:49], off
	v_mfma_f32_32x32x16_bf16 v[80:95], v[186:189], v[100:103], v[80:95]
	s_waitcnt lgkmcnt(5)
	v_mfma_f32_32x32x16_bf16 v[64:79], v[218:221], v[100:103], v[64:79]
	v_mfma_f32_32x32x16_bf16 v[80:95], v[190:193], v[96:99], v[80:95]
	s_waitcnt lgkmcnt(4)
	v_mfma_f32_32x32x16_bf16 v[64:79], v[222:225], v[96:99], v[64:79]
	s_setprio 0
	s_nop 8
	v_max3_f32 v48, v80, v81, v82
	s_nop 0
	v_max3_f32 v49, v64, v65, v66
	v_max3_f32 v48, v48, v83, v84
	v_max3_f32 v49, v49, v67, v68
	v_max3_f32 v48, v48, v85, v86
	v_max3_f32 v49, v49, v69, v70
	v_max3_f32 v48, v48, v87, v88
	v_max3_f32 v49, v49, v71, v72
	v_max3_f32 v48, v48, v89, v90
	v_max3_f32 v49, v49, v73, v74
	v_max3_f32 v48, v48, v91, v92
	v_max3_f32 v49, v49, v75, v76
	v_max_f32_e32 v50, v79, v79
	v_max_f32_e32 v51, v95, v95
	v_max3_f32 v48, v48, v93, v94
	v_max3_f32 v49, v49, v77, v78
	v_max_f32_e32 v50, v51, v50
	v_max3_f32 v48, v48, v49, v50
	v_cmp_lt_f32_e32 vcc, s33, v48
	s_cbranch_vccz .LBB0_712
; __device__ __forceinline__ float shx(float v, int mask, int lane) { return __int_as_float(__builtin_amdgcn_ds_bpermute((lane ^ mask) << 2, __float_as_int(v))); }
; template <bool DIFF> ...
;     ...
;             mx = fmaxf(mx, shx(mx, 32, lane));
;             if (t == 0 || __any(mx > 8.0f)) {
;                 const float dl = (t == 0) ? mx : fmaxf(mx, 0.f);
;                 mrun += dl;
; #pragma unroll
;                 for (int r = 0; r < 16; ++r) negm[r] = -mrun;
;                 const float alpha = (t == 0) ? 1.f : __builtin_amdgcn_exp2f(-dl); lsum *= alpha;
; #pragma unroll
;                 for (int kb = 0; kb < 2; ++kb) pr[kb] = pr[kb] - dl;
; #pragma unroll
;                 for (int db = 0; db < NDB; ++db) o[db] = o[db] * alpha;
;             }
;             f32x2 ps2 = (f32x2){0.f, 0.f};
; #pragma unroll
;             for (int kb = 0; kb < 2; ++kb)
; #pragma unroll
;                 for (int r = 0; r < 16; r += 2) { const float e0 = __builtin_amdgcn_exp2f(pr[kb][r]), e1 = __builtin_amdgcn_exp2f(pr[kb][r + 1]); pr[kb][r] = e0; pr[kb][r + 1] = e1; ps2 += (f32x2){e0, e1}; }
;             lsum += ps2[0] + ps2[1];
;             __builtin_amdgcn_sched_barrier(0);
;             VLOAD(vfb, 1); __builtin_amdgcn_sched_barrier(0); PVMMA(vfa, 0); __builtin_amdgcn_sched_barrier(0);
;             VLOAD(vfa, 2); __builtin_amdgcn_sched_barrier(0); PVMMA(vfb, 1); __builtin_amdgcn_sched_barrier(0);
;             VLOAD(vfb, 3); __builtin_amdgcn_sched_barrier(0); PVMMA(vfa, 2); __builtin_amdgcn_sched_barrier(0);
;             PVMMA(vfb, 3);
;     ...
;         }
;         if (t + 1 < NT) ATT_LSTORE(buf ^ 1);
;         __syncthreads();
	ds_bpermute_b32 v49, v163, v48
	s_waitcnt lgkmcnt(0)
	v_max_f32_e32 v49, v49, v49
	v_max_f32_e32 v48, v48, v49
	v_max_f32_e32 v32, v48, v48
	v_max_f32_e32 v33, 0, v32
	v_exp_f32_e64 v34, -v33
	v_add_f32_e32 v152, v152, v33
	v_xor_b32_e32 v32, 0x80000000, v152
	v_sub_f32_e32 v80, v80, v33
	v_sub_f32_e32 v81, v81, v33
	v_sub_f32_e32 v82, v82, v33
	v_sub_f32_e32 v95, v95, v33
	v_sub_f32_e32 v83, v83, v33
	v_sub_f32_e32 v84, v84, v33
	v_sub_f32_e32 v85, v85, v33
	v_sub_f32_e32 v86, v86, v33
	v_sub_f32_e32 v87, v87, v33
	v_sub_f32_e32 v88, v88, v33
	v_sub_f32_e32 v89, v89, v33
	v_sub_f32_e32 v90, v90, v33
	v_sub_f32_e32 v91, v91, v33
	v_sub_f32_e32 v92, v92, v33
	v_sub_f32_e32 v93, v93, v33
	v_sub_f32_e32 v94, v94, v33
	v_sub_f32_e32 v64, v64, v33
	v_sub_f32_e32 v65, v65, v33
	v_sub_f32_e32 v66, v66, v33
	v_sub_f32_e32 v67, v67, v33
	v_sub_f32_e32 v68, v68, v33
	v_sub_f32_e32 v69, v69, v33
	v_sub_f32_e32 v70, v70, v33
	v_sub_f32_e32 v71, v71, v33
	v_sub_f32_e32 v72, v72, v33
	v_sub_f32_e32 v73, v73, v33
	v_sub_f32_e32 v74, v74, v33
	v_sub_f32_e32 v75, v75, v33
	v_sub_f32_e32 v76, v76, v33
	v_sub_f32_e32 v77, v77, v33
	v_sub_f32_e32 v78, v78, v33
	v_sub_f32_e32 v79, v79, v33
	v_pk_mul_f32 v[30:31], v[30:31], v[34:35] op_sel_hi:[1,0]
	v_pk_mul_f32 v[28:29], v[28:29], v[34:35] op_sel_hi:[1,0]
	v_pk_mul_f32 v[26:27], v[26:27], v[34:35] op_sel_hi:[1,0]
	v_pk_mul_f32 v[24:25], v[24:25], v[34:35] op_sel_hi:[1,0]
	v_pk_mul_f32 v[22:23], v[22:23], v[34:35] op_sel_hi:[1,0]
	v_pk_mul_f32 v[20:21], v[20:21], v[34:35] op_sel_hi:[1,0]
	v_pk_mul_f32 v[18:19], v[18:19], v[34:35] op_sel_hi:[1,0]
	v_pk_mul_f32 v[16:17], v[16:17], v[34:35] op_sel_hi:[1,0]
	v_pk_mul_f32 v[14:15], v[14:15], v[34:35] op_sel_hi:[1,0]
	v_pk_mul_f32 v[12:13], v[12:13], v[34:35] op_sel_hi:[1,0]
	v_pk_mul_f32 v[10:11], v[10:11], v[34:35] op_sel_hi:[1,0]
	v_pk_mul_f32 v[8:9], v[8:9], v[34:35] op_sel_hi:[1,0]
	v_pk_mul_f32 v[6:7], v[6:7], v[34:35] op_sel_hi:[1,0]
	v_pk_mul_f32 v[4:5], v[4:5], v[34:35] op_sel_hi:[1,0]
	v_pk_mul_f32 v[2:3], v[2:3], v[34:35] op_sel_hi:[1,0]
	v_pk_mul_f32 v[0:1], v[0:1], v[34:35] op_sel_hi:[1,0]
	v_mul_f32_e32 v153, v153, v34
	v_mov_b32_e32 v33, v32
	v_mov_b32_e32 v34, v32
	v_mov_b32_e32 v35, v32
	v_mov_b32_e32 v36, v32
	v_mov_b32_e32 v37, v32
	v_mov_b32_e32 v38, v32
	v_mov_b32_e32 v39, v32
	v_mov_b32_e32 v40, v32
	v_mov_b32_e32 v41, v32
	v_mov_b32_e32 v42, v32
	v_mov_b32_e32 v43, v32
	v_mov_b32_e32 v44, v32
	v_mov_b32_e32 v45, v32
	v_mov_b32_e32 v46, v32
	v_mov_b32_e32 v47, v32
	s_branch .LBB0_713
.LBB0_712:
.LBB0_713:
	ds_read_b64_tr_b16 v[202:203], v185 offset:30720
	ds_read_b64_tr_b16 v[204:205], v185 offset:33280
	ds_read_b64_tr_b16 v[206:207], v185 offset:30784
	ds_read_b64_tr_b16 v[208:209], v185 offset:33344
	v_exp_f32_e32 v210, v80
	v_exp_f32_e32 v211, v81
	v_exp_f32_e32 v212, v82
	v_exp_f32_e32 v213, v83
	v_pk_add_f32 v[54:55], v[210:211], 0 op_sel_hi:[1,0]
	v_exp_f32_e32 v214, v84
	v_exp_f32_e32 v215, v85
	v_pk_add_f32 v[54:55], v[212:213], v[54:55]
	v_exp_f32_e32 v80, v86
	v_exp_f32_e32 v81, v87
	v_pk_add_f32 v[54:55], v[214:215], v[54:55]
	v_cvt_pk_bf16_f32 v216, v210, v211
	v_cvt_pk_bf16_f32 v217, v212, v213
	v_cvt_pk_bf16_f32 v218, v214, v215
	v_cvt_pk_bf16_f32 v219, v80, v81
	s_setprio 1
	v_pk_add_f32 v[54:55], v[80:81], v[54:55]
	s_waitcnt lgkmcnt(4)
	v_mfma_f32_32x32x16_bf16 v[16:31], v[142:145], v[216:219], v[16:31]
	v_exp_f32_e32 v82, v88
	v_exp_f32_e32 v83, v89
	v_exp_f32_e32 v84, v90
	v_exp_f32_e32 v85, v91
	v_pk_add_f32 v[54:55], v[82:83], v[54:55]
	v_mfma_f32_32x32x16_bf16 v[0:15], v[146:149], v[216:219], v[0:15]
	v_exp_f32_e32 v86, v92
	v_exp_f32_e32 v87, v93
	v_exp_f32_e32 v88, v94
	v_exp_f32_e32 v89, v95
	v_pk_add_f32 v[54:55], v[84:85], v[54:55]
	v_pk_add_f32 v[54:55], v[86:87], v[54:55]
	ds_read_b64_tr_b16 v[220:221], v185 offset:35840
	ds_read_b64_tr_b16 v[222:223], v185 offset:38400
	ds_read_b64_tr_b16 v[226:227], v185 offset:38464
	ds_read_b64_tr_b16 v[224:225], v185 offset:35904
	v_cvt_pk_bf16_f32 v228, v82, v83
	v_cvt_pk_bf16_f32 v229, v84, v85
	v_cvt_pk_bf16_f32 v230, v86, v87
	v_cvt_pk_bf16_f32 v231, v88, v89
	v_pk_add_f32 v[54:55], v[88:89], v[54:55]
	s_waitcnt lgkmcnt(6)
	v_mfma_f32_32x32x16_bf16 v[16:31], v[202:205], v[228:231], v[16:31]
	v_exp_f32_e32 v90, v64
	v_exp_f32_e32 v91, v65
	v_exp_f32_e32 v92, v66
	v_exp_f32_e32 v93, v67
	v_pk_add_f32 v[54:55], v[90:91], v[54:55]
	s_waitcnt lgkmcnt(4)
	v_mfma_f32_32x32x16_bf16 v[0:15], v[206:209], v[228:231], v[0:15]
	v_exp_f32_e32 v94, v68
	v_exp_f32_e32 v95, v69
	v_exp_f32_e32 v198, v70
	v_exp_f32_e32 v199, v71
	v_pk_add_f32 v[54:55], v[92:93], v[54:55]
	v_pk_add_f32 v[54:55], v[94:95], v[54:55]
	ds_read_b64_tr_b16 v[202:203], v185 offset:40960
	ds_read_b64_tr_b16 v[204:205], v185 offset:43520
	ds_read_b64_tr_b16 v[208:209], v185 offset:43584
	ds_read_b64_tr_b16 v[206:207], v185 offset:41024
	v_cvt_pk_bf16_f32 v228, v90, v91
	v_cvt_pk_bf16_f32 v229, v92, v93
	v_cvt_pk_bf16_f32 v230, v94, v95
	v_cvt_pk_bf16_f32 v231, v198, v199
	v_pk_add_f32 v[54:55], v[198:199], v[54:55]
	s_waitcnt lgkmcnt(6)
	v_mfma_f32_32x32x16_bf16 v[16:31], v[220:223], v[228:231], v[16:31]
	v_exp_f32_e32 v72, v72
	v_exp_f32_e32 v73, v73
	v_exp_f32_e32 v74, v74
	v_exp_f32_e32 v75, v75
	v_pk_add_f32 v[54:55], v[72:73], v[54:55]
	s_waitcnt lgkmcnt(4)
	v_mfma_f32_32x32x16_bf16 v[0:15], v[224:227], v[228:231], v[0:15]
	v_exp_f32_e32 v76, v76
	v_exp_f32_e32 v77, v77
	v_exp_f32_e32 v78, v78
	v_exp_f32_e32 v79, v79
	v_pk_add_f32 v[54:55], v[74:75], v[54:55]
	v_pk_add_f32 v[54:55], v[76:77], v[54:55]
	v_cvt_pk_bf16_f32 v216, v72, v73
	v_cvt_pk_bf16_f32 v217, v74, v75
	v_cvt_pk_bf16_f32 v218, v76, v77
	v_cvt_pk_bf16_f32 v219, v78, v79
	v_pk_add_f32 v[54:55], v[78:79], v[54:55]
	s_nop 0
	v_add_f32_e32 v52, v54, v55
	s_waitcnt lgkmcnt(2)
	v_mfma_f32_32x32x16_bf16 v[16:31], v[202:205], v[216:219], v[16:31]
	v_add_f32_e32 v153, v153, v52
	s_xor_b32 s16, s1, 1
	s_mul_i32 s16, s16, 0xb400
	v_add3_u32 v64, s16, v164, v165
	s_waitcnt vmcnt(4)
	ds_write_b128 v64, v[124:127]
	v_add3_u32 v64, s16, v166, v167
	s_waitcnt vmcnt(3)
	ds_write_b128 v64, v[120:123]
	s_waitcnt lgkmcnt(2)
	v_mfma_f32_32x32x16_bf16 v[0:15], v[206:209], v[216:219], v[0:15]
	v_add3_u32 v64, s16, v168, v169
	s_waitcnt vmcnt(2)
	ds_write_b128 v64, v[134:137]
	v_add_u32_e32 v64, s16, v128
	v_add_u32_e32 v65, v64, v170
	v_add_u32_e32 v64, v64, v171
	s_waitcnt vmcnt(1)
	ds_write_b128 v65, v[130:133] offset:25600
	s_waitcnt vmcnt(0)
	ds_write_b128 v64, v[138:141] offset:25600
	s_setprio 0
	s_branch .Ltail2_m2
